# K-loops: B0 fragment ds_reads moved from phase 1/5 to the end of phase 8/4 load segments (max 8 LDS reads per segment), counted vmcnt(10) at phases 3/7 retire the B0 buffers one phase earlier
# speedup vs baseline: 1.0010x; 1.0010x over previous
.LBB0_266:
	s_xor_b64 s[2:3], s[2:3], -1
	s_mov_b32 s34, s74
	s_add_i32 s74, s74, 1
	s_cmp_lt_u32 s34, 5
	s_mov_b64 s[4:5], s[10:11]
	s_mov_b32 s10, s75
	s_cselect_b64 s[14:15], -1, 0
	s_add_i32 s75, s74, s16
	s_mov_b64 s[12:13], s[8:9]
	s_and_b64 s[8:9], s[14:15], exec
	s_cselect_b32 s8, s75, s10
	s_cselect_b32 s10, s6, s6
	s_ashr_i32 s11, s10, 31
	s_lshl_b64 s[10:11], s[10:11], 19
	s_add_u32 s10, s80, s10
	s_addc_u32 s11, s81, s11
	s_and_b64 s[44:45], s[14:15], exec
	s_cselect_b32 s44, s11, s5
	s_cselect_b32 s45, s10, s4
	s_ashr_i32 s9, s8, 31
	s_lshl_b64 s[8:9], s[8:9], 19
	v_readlane_b32 s47, v255, 14
	s_add_u32 s8, s47, s8
	v_readlane_b32 s47, v255, 15
	s_addc_u32 s9, s47, s9
	s_and_b64 s[14:15], s[14:15], exec
	s_cselect_b32 s47, s9, s13
	s_cselect_b32 s55, s8, s12
	s_add_u32 s4, s4, 0x40080
	s_addc_u32 s5, s5, 0
	s_add_u32 s78, s12, 0x100
	v_mov_b32_e32 v2, 0
	s_addc_u32 s79, s13, 0
	s_mov_b32 s85, -2
	v_mov_b32_e32 v3, v2
	s_waitcnt lgkmcnt(0)
	v_mov_b32_e32 v4, v2
	v_mov_b32_e32 v5, v2
	v_mov_b32_e32 v6, v2
	v_mov_b32_e32 v7, v2
	v_mov_b32_e32 v8, v2
	v_mov_b32_e32 v9, v2
	v_mov_b32_e32 v18, v2
	v_mov_b32_e32 v19, v2
	v_mov_b32_e32 v20, v2
	v_mov_b32_e32 v21, v2
	v_mov_b32_e32 v22, v2
	v_mov_b32_e32 v23, v2
	v_mov_b32_e32 v24, v2
	v_mov_b32_e32 v25, v2
	v_mov_b32_e32 v34, v2
	v_mov_b32_e32 v35, v2
	v_mov_b32_e32 v36, v2
	v_mov_b32_e32 v37, v2
	v_mov_b32_e32 v38, v2
	v_mov_b32_e32 v39, v2
	v_mov_b32_e32 v40, v2
	v_mov_b32_e32 v41, v2
	v_mov_b32_e32 v50, v2
	v_mov_b32_e32 v51, v2
	v_mov_b32_e32 v52, v2
	v_mov_b32_e32 v53, v2
	v_mov_b32_e32 v54, v2
	v_mov_b32_e32 v55, v2
	v_mov_b32_e32 v56, v2
	v_mov_b32_e32 v57, v2
	v_mov_b32_e32 v10, v2
	v_mov_b32_e32 v11, v2
	v_mov_b32_e32 v12, v2
	v_mov_b32_e32 v13, v2
	v_mov_b32_e32 v14, v2
	v_mov_b32_e32 v15, v2
	v_mov_b32_e32 v16, v2
	v_mov_b32_e32 v17, v2
	v_mov_b32_e32 v26, v2
	v_mov_b32_e32 v27, v2
	v_mov_b32_e32 v28, v2
	v_mov_b32_e32 v29, v2
	v_mov_b32_e32 v30, v2
	v_mov_b32_e32 v31, v2
	v_mov_b32_e32 v32, v2
	v_mov_b32_e32 v33, v2
	v_mov_b32_e32 v42, v2
	v_mov_b32_e32 v43, v2
	v_mov_b32_e32 v44, v2
	v_mov_b32_e32 v45, v2
	v_mov_b32_e32 v46, v2
	v_mov_b32_e32 v47, v2
	v_mov_b32_e32 v48, v2
	v_mov_b32_e32 v49, v2
	v_mov_b32_e32 v58, v2
	v_mov_b32_e32 v59, v2
	v_mov_b32_e32 v60, v2
	v_mov_b32_e32 v61, v2
	v_mov_b32_e32 v62, v2
	v_mov_b32_e32 v63, v2
	v_mov_b32_e32 v64, v2
	v_mov_b32_e32 v65, v2
	v_mov_b32_e32 v66, v2
	v_mov_b32_e32 v67, v2
	v_mov_b32_e32 v68, v2
	v_mov_b32_e32 v69, v2
	v_mov_b32_e32 v70, v2
	v_mov_b32_e32 v71, v2
	v_mov_b32_e32 v72, v2
	v_mov_b32_e32 v73, v2
	v_mov_b32_e32 v82, v2
	v_mov_b32_e32 v83, v2
	v_mov_b32_e32 v84, v2
	v_mov_b32_e32 v85, v2
	v_mov_b32_e32 v86, v2
	v_mov_b32_e32 v87, v2
	v_mov_b32_e32 v88, v2
	v_mov_b32_e32 v89, v2
	v_mov_b32_e32 v98, v2
	v_mov_b32_e32 v99, v2
	v_mov_b32_e32 v100, v2
	v_mov_b32_e32 v101, v2
	v_mov_b32_e32 v102, v2
	v_mov_b32_e32 v103, v2
	v_mov_b32_e32 v104, v2
	v_mov_b32_e32 v105, v2
	v_mov_b32_e32 v114, v2
	v_mov_b32_e32 v115, v2
	v_mov_b32_e32 v116, v2
	v_mov_b32_e32 v117, v2
	v_mov_b32_e32 v118, v2
	v_mov_b32_e32 v119, v2
	v_mov_b32_e32 v120, v2
	v_mov_b32_e32 v121, v2
	v_mov_b32_e32 v74, v2
	v_mov_b32_e32 v75, v2
	v_mov_b32_e32 v76, v2
	v_mov_b32_e32 v77, v2
	v_mov_b32_e32 v78, v2
	v_mov_b32_e32 v79, v2
	v_mov_b32_e32 v80, v2
	v_mov_b32_e32 v81, v2
	v_mov_b32_e32 v90, v2
	v_mov_b32_e32 v91, v2
	v_mov_b32_e32 v92, v2
	v_mov_b32_e32 v93, v2
	v_mov_b32_e32 v94, v2
	v_mov_b32_e32 v95, v2
	v_mov_b32_e32 v96, v2
	v_mov_b32_e32 v97, v2
	v_mov_b32_e32 v106, v2
	v_mov_b32_e32 v107, v2
	v_mov_b32_e32 v108, v2
	v_mov_b32_e32 v109, v2
	v_mov_b32_e32 v110, v2
	v_mov_b32_e32 v111, v2
	v_mov_b32_e32 v112, v2
	v_mov_b32_e32 v113, v2
	v_mov_b32_e32 v122, v2
	v_mov_b32_e32 v123, v2
	v_mov_b32_e32 v124, v2
	v_mov_b32_e32 v125, v2
	v_mov_b32_e32 v126, v2
	v_mov_b32_e32 v127, v2
	v_mov_b32_e32 v128, v2
	v_mov_b32_e32 v129, v2
	s_add_i32 s86, 0, 0x10000
	v_add_u32_e32 v0, s86, v150
	ds_read_b128 v[142:145], v0
	ds_read_b128 v[146:149], v0 offset:1024
	ds_read_b128 v[152:155], v0 offset:2048
	ds_read_b128 v[156:159], v0 offset:3072
.LBB0_267:
	s_add_u32 s12, s4, 0xfffc0080
	s_addc_u32 s13, s5, -1
	s_cmp_eq_u32 s85, 12
	s_cselect_b32 s15, s44, s13
	s_cselect_b32 s14, s45, s12
	s_cselect_b32 s13, s47, s79
	s_cselect_b32 s12, s55, s78
	v_lshl_add_u64 v[194:195], s[4:5], 0, v[138:139]
	s_add_i32 m0, s7, 0xc000
	ds_read_b128 v[160:163], v151
	ds_read_b128 v[164:167], v151 offset:1024
	ds_read_b128 v[168:171], v151 offset:2048
	ds_read_b128 v[172:175], v151 offset:3072
	ds_read_b128 v[176:179], v151 offset:4096
	ds_read_b128 v[180:183], v151 offset:5120
	ds_read_b128 v[184:187], v151 offset:6144
	ds_read_b128 v[190:193], v151 offset:7168
	global_load_lds_dwordx4 v[194:195], off
	s_add_i32 m0, s7, 0xe000
	v_lshl_add_u64 v[194:195], s[4:5], 0, v[140:141]
	global_load_lds_dwordx4 v[194:195], off
	s_waitcnt lgkmcnt(8)
	s_barrier
	s_waitcnt lgkmcnt(0)
	v_mfma_f32_16x16x32_bf16 v[126:129], v[142:145], v[160:163], v[126:129]
	v_mfma_f32_16x16x32_bf16 v[122:125], v[152:155], v[160:163], v[122:125]
	v_mfma_f32_16x16x32_bf16 v[110:113], v[142:145], v[168:171], v[110:113]
	v_mfma_f32_16x16x32_bf16 v[106:109], v[152:155], v[168:171], v[106:109]
	v_mfma_f32_16x16x32_bf16 v[94:97], v[142:145], v[176:179], v[94:97]
	v_mfma_f32_16x16x32_bf16 v[90:93], v[152:155], v[176:179], v[90:93]
	v_mfma_f32_16x16x32_bf16 v[78:81], v[142:145], v[184:187], v[78:81]
	v_mfma_f32_16x16x32_bf16 v[74:77], v[152:155], v[184:187], v[74:77]
	v_mfma_f32_16x16x32_bf16 v[126:129], v[146:149], v[164:167], v[126:129]
	v_mfma_f32_16x16x32_bf16 v[122:125], v[156:159], v[164:167], v[122:125]
	v_mfma_f32_16x16x32_bf16 v[110:113], v[146:149], v[172:175], v[110:113]
	v_mfma_f32_16x16x32_bf16 v[106:109], v[156:159], v[172:175], v[106:109]
	v_mfma_f32_16x16x32_bf16 v[94:97], v[146:149], v[180:183], v[94:97]
	v_mfma_f32_16x16x32_bf16 v[90:93], v[156:159], v[180:183], v[90:93]
	v_mfma_f32_16x16x32_bf16 v[78:81], v[146:149], v[190:193], v[78:81]
	v_mfma_f32_16x16x32_bf16 v[74:77], v[156:159], v[190:193], v[74:77]
	s_barrier
	s_add_i32 s88, 0, 0x14000
	s_add_i32 s86, s86, s22
	v_add_u32_e32 v0, s88, v150
	v_lshl_add_u64 v[210:211], s[12:13], 0, v[134:135]
	s_mov_b32 m0, s86
	ds_read_b128 v[194:197], v0
	ds_read_b128 v[198:201], v0 offset:1024
	ds_read_b128 v[202:205], v0 offset:2048
	ds_read_b128 v[206:209], v0 offset:3072
	global_load_lds_dwordx4 v[210:211], off
	s_add_i32 m0, s86, 0x2000
	v_lshl_add_u64 v[212:213], s[12:13], 0, v[130:131]
	global_load_lds_dwordx4 v[212:213], off
	s_barrier
	s_waitcnt lgkmcnt(0)
	v_mfma_f32_16x16x32_bf16 v[118:121], v[194:197], v[160:163], v[118:121]
	v_mfma_f32_16x16x32_bf16 v[114:117], v[202:205], v[160:163], v[114:117]
	v_mfma_f32_16x16x32_bf16 v[102:105], v[194:197], v[168:171], v[102:105]
	v_mfma_f32_16x16x32_bf16 v[98:101], v[202:205], v[168:171], v[98:101]
	v_mfma_f32_16x16x32_bf16 v[86:89], v[194:197], v[176:179], v[86:89]
	v_mfma_f32_16x16x32_bf16 v[82:85], v[202:205], v[176:179], v[82:85]
	v_mfma_f32_16x16x32_bf16 v[70:73], v[194:197], v[184:187], v[70:73]
	v_mfma_f32_16x16x32_bf16 v[66:69], v[202:205], v[184:187], v[66:69]
	v_mfma_f32_16x16x32_bf16 v[118:121], v[198:201], v[164:167], v[118:121]
	v_mfma_f32_16x16x32_bf16 v[114:117], v[206:209], v[164:167], v[114:117]
	v_mfma_f32_16x16x32_bf16 v[102:105], v[198:201], v[172:175], v[102:105]
	v_mfma_f32_16x16x32_bf16 v[98:101], v[206:209], v[172:175], v[98:101]
	v_mfma_f32_16x16x32_bf16 v[86:89], v[198:201], v[180:183], v[86:89]
	v_mfma_f32_16x16x32_bf16 v[82:85], v[206:209], v[180:183], v[82:85]
	v_mfma_f32_16x16x32_bf16 v[70:73], v[198:201], v[190:193], v[70:73]
	v_mfma_f32_16x16x32_bf16 v[66:69], v[206:209], v[190:193], v[66:69]
	s_mov_b32 m0, s7
	v_lshl_add_u64 v[214:215], s[14:15], 0, v[136:137]
	s_barrier
	ds_read_b128 v[160:163], v151 offset:16384
	ds_read_b128 v[164:167], v151 offset:17408
	ds_read_b128 v[168:171], v151 offset:18432
	ds_read_b128 v[172:175], v151 offset:19456
	ds_read_b128 v[176:179], v151 offset:20480
	ds_read_b128 v[180:183], v151 offset:21504
	ds_read_b128 v[184:187], v151 offset:22528
	ds_read_b128 v[190:193], v151 offset:23552
	global_load_lds_dwordx4 v[214:215], off
	s_mov_b32 m0, s23
	v_lshl_add_u64 v[216:217], s[14:15], 0, v[132:133]
	global_load_lds_dwordx4 v[216:217], off
	s_waitcnt vmcnt(10)
	s_barrier
	s_waitcnt lgkmcnt(0)
	v_mfma_f32_16x16x32_bf16 v[62:65], v[142:145], v[160:163], v[62:65]
	v_mfma_f32_16x16x32_bf16 v[58:61], v[152:155], v[160:163], v[58:61]
	v_mfma_f32_16x16x32_bf16 v[46:49], v[142:145], v[168:171], v[46:49]
	v_mfma_f32_16x16x32_bf16 v[42:45], v[152:155], v[168:171], v[42:45]
	v_mfma_f32_16x16x32_bf16 v[30:33], v[142:145], v[176:179], v[30:33]
	v_mfma_f32_16x16x32_bf16 v[26:29], v[152:155], v[176:179], v[26:29]
	v_mfma_f32_16x16x32_bf16 v[14:17], v[142:145], v[184:187], v[14:17]
	v_mfma_f32_16x16x32_bf16 v[10:13], v[152:155], v[184:187], v[10:13]
	v_mfma_f32_16x16x32_bf16 v[62:65], v[146:149], v[164:167], v[62:65]
	v_mfma_f32_16x16x32_bf16 v[58:61], v[156:159], v[164:167], v[58:61]
	v_mfma_f32_16x16x32_bf16 v[46:49], v[146:149], v[172:175], v[46:49]
	v_mfma_f32_16x16x32_bf16 v[42:45], v[156:159], v[172:175], v[42:45]
	v_mfma_f32_16x16x32_bf16 v[30:33], v[146:149], v[180:183], v[30:33]
	v_mfma_f32_16x16x32_bf16 v[26:29], v[156:159], v[180:183], v[26:29]
	v_mfma_f32_16x16x32_bf16 v[14:17], v[146:149], v[190:193], v[14:17]
	v_mfma_f32_16x16x32_bf16 v[10:13], v[156:159], v[190:193], v[10:13]
	s_barrier
	s_add_u32 s86, s12, 0x40000
	s_addc_u32 s87, s13, 0
	s_add_i32 s88, s88, s22
	s_mov_b32 m0, s88
	v_lshl_add_u64 v[142:143], s[86:87], 0, v[134:135]
	global_load_lds_dwordx4 v[142:143], off
	s_add_i32 m0, s88, 0x2000
	v_lshl_add_u64 v[142:143], s[86:87], 0, v[130:131]
	global_load_lds_dwordx4 v[142:143], off
	s_add_i32 s86, 0, 0x18000
	v_add_u32_e32 v0, s86, v150
	ds_read_b128 v[142:145], v0
	ds_read_b128 v[146:149], v0 offset:1024
	ds_read_b128 v[152:155], v0 offset:2048
	ds_read_b128 v[156:159], v0 offset:3072
	s_waitcnt vmcnt(6)
	s_barrier
	v_mfma_f32_16x16x32_bf16 v[54:57], v[194:197], v[160:163], v[54:57]
	v_mfma_f32_16x16x32_bf16 v[50:53], v[202:205], v[160:163], v[50:53]
	v_mfma_f32_16x16x32_bf16 v[38:41], v[194:197], v[168:171], v[38:41]
	v_mfma_f32_16x16x32_bf16 v[34:37], v[202:205], v[168:171], v[34:37]
	v_mfma_f32_16x16x32_bf16 v[22:25], v[194:197], v[176:179], v[22:25]
	v_mfma_f32_16x16x32_bf16 v[18:21], v[202:205], v[176:179], v[18:21]
	v_mfma_f32_16x16x32_bf16 v[6:9], v[194:197], v[184:187], v[6:9]
	v_mfma_f32_16x16x32_bf16 v[2:5], v[202:205], v[184:187], v[2:5]
	v_mfma_f32_16x16x32_bf16 v[54:57], v[198:201], v[164:167], v[54:57]
	v_mfma_f32_16x16x32_bf16 v[50:53], v[206:209], v[164:167], v[50:53]
	v_mfma_f32_16x16x32_bf16 v[38:41], v[198:201], v[172:175], v[38:41]
	v_mfma_f32_16x16x32_bf16 v[34:37], v[206:209], v[172:175], v[34:37]
	v_mfma_f32_16x16x32_bf16 v[22:25], v[198:201], v[180:183], v[22:25]
	v_mfma_f32_16x16x32_bf16 v[18:21], v[206:209], v[180:183], v[18:21]
	v_mfma_f32_16x16x32_bf16 v[6:9], v[198:201], v[190:193], v[6:9]
	v_mfma_f32_16x16x32_bf16 v[2:5], v[206:209], v[190:193], v[2:5]
	s_barrier
	s_add_u32 s14, s14, 0x40000
	s_addc_u32 s15, s15, 0
	s_mov_b32 m0, s28
	v_lshl_add_u64 v[194:195], s[14:15], 0, v[136:137]
	ds_read_b128 v[160:163], v151 offset:32768
	ds_read_b128 v[164:167], v151 offset:33792
	ds_read_b128 v[168:171], v151 offset:34816
	ds_read_b128 v[172:175], v151 offset:35840
	ds_read_b128 v[176:179], v151 offset:36864
	ds_read_b128 v[180:183], v151 offset:37888
	ds_read_b128 v[184:187], v151 offset:38912
	ds_read_b128 v[190:193], v151 offset:39936
	global_load_lds_dwordx4 v[194:195], off
	s_mov_b32 m0, s29
	v_lshl_add_u64 v[194:195], s[14:15], 0, v[132:133]
	global_load_lds_dwordx4 v[194:195], off
	s_waitcnt lgkmcnt(8)
	s_barrier
	s_waitcnt lgkmcnt(0)
	v_mfma_f32_16x16x32_bf16 v[126:129], v[142:145], v[160:163], v[126:129]
	v_mfma_f32_16x16x32_bf16 v[122:125], v[152:155], v[160:163], v[122:125]
	v_mfma_f32_16x16x32_bf16 v[110:113], v[142:145], v[168:171], v[110:113]
	v_mfma_f32_16x16x32_bf16 v[106:109], v[152:155], v[168:171], v[106:109]
	v_mfma_f32_16x16x32_bf16 v[94:97], v[142:145], v[176:179], v[94:97]
	v_mfma_f32_16x16x32_bf16 v[90:93], v[152:155], v[176:179], v[90:93]
	v_mfma_f32_16x16x32_bf16 v[78:81], v[142:145], v[184:187], v[78:81]
	v_mfma_f32_16x16x32_bf16 v[74:77], v[152:155], v[184:187], v[74:77]
	v_mfma_f32_16x16x32_bf16 v[126:129], v[146:149], v[164:167], v[126:129]
	v_mfma_f32_16x16x32_bf16 v[122:125], v[156:159], v[164:167], v[122:125]
	v_mfma_f32_16x16x32_bf16 v[110:113], v[146:149], v[172:175], v[110:113]
	v_mfma_f32_16x16x32_bf16 v[106:109], v[156:159], v[172:175], v[106:109]
	v_mfma_f32_16x16x32_bf16 v[94:97], v[146:149], v[180:183], v[94:97]
	v_mfma_f32_16x16x32_bf16 v[90:93], v[156:159], v[180:183], v[90:93]
	v_mfma_f32_16x16x32_bf16 v[78:81], v[146:149], v[190:193], v[78:81]
	v_mfma_f32_16x16x32_bf16 v[74:77], v[156:159], v[190:193], v[74:77]
	s_barrier
	s_add_i32 s14, 0, 0x1c000
	s_add_i32 s15, s86, s22
	v_add_u32_e32 v0, s14, v150
	v_lshl_add_u64 v[210:211], v[210:211], 0, s[40:41]
	s_mov_b32 m0, s15
	ds_read_b128 v[194:197], v0
	ds_read_b128 v[198:201], v0 offset:1024
	ds_read_b128 v[202:205], v0 offset:2048
	ds_read_b128 v[206:209], v0 offset:3072
	global_load_lds_dwordx4 v[210:211], off
	s_add_i32 m0, s15, 0x2000
	v_lshl_add_u64 v[210:211], v[212:213], 0, s[40:41]
	global_load_lds_dwordx4 v[210:211], off
	s_barrier
	s_waitcnt lgkmcnt(0)
	v_mfma_f32_16x16x32_bf16 v[118:121], v[194:197], v[160:163], v[118:121]
	v_mfma_f32_16x16x32_bf16 v[114:117], v[202:205], v[160:163], v[114:117]
	v_mfma_f32_16x16x32_bf16 v[102:105], v[194:197], v[168:171], v[102:105]
	v_mfma_f32_16x16x32_bf16 v[98:101], v[202:205], v[168:171], v[98:101]
	v_mfma_f32_16x16x32_bf16 v[86:89], v[194:197], v[176:179], v[86:89]
	v_mfma_f32_16x16x32_bf16 v[82:85], v[202:205], v[176:179], v[82:85]
	v_mfma_f32_16x16x32_bf16 v[70:73], v[194:197], v[184:187], v[70:73]
	v_mfma_f32_16x16x32_bf16 v[66:69], v[202:205], v[184:187], v[66:69]
	v_mfma_f32_16x16x32_bf16 v[118:121], v[198:201], v[164:167], v[118:121]
	v_mfma_f32_16x16x32_bf16 v[114:117], v[206:209], v[164:167], v[114:117]
	v_mfma_f32_16x16x32_bf16 v[102:105], v[198:201], v[172:175], v[102:105]
	v_mfma_f32_16x16x32_bf16 v[98:101], v[206:209], v[172:175], v[98:101]
	v_mfma_f32_16x16x32_bf16 v[86:89], v[198:201], v[180:183], v[86:89]
	v_mfma_f32_16x16x32_bf16 v[82:85], v[206:209], v[180:183], v[82:85]
	v_mfma_f32_16x16x32_bf16 v[70:73], v[198:201], v[190:193], v[70:73]
	v_mfma_f32_16x16x32_bf16 v[66:69], v[206:209], v[190:193], v[66:69]
	s_mov_b32 m0, s38
	v_lshl_add_u64 v[210:211], v[214:215], 0, s[40:41]
	s_barrier
	ds_read_b128 v[160:163], v151 offset:49152
	ds_read_b128 v[164:167], v151 offset:50176
	ds_read_b128 v[168:171], v151 offset:51200
	ds_read_b128 v[172:175], v151 offset:52224
	ds_read_b128 v[176:179], v151 offset:53248
	ds_read_b128 v[180:183], v151 offset:54272
	ds_read_b128 v[184:187], v151 offset:55296
	ds_read_b128 v[190:193], v151 offset:56320
	global_load_lds_dwordx4 v[210:211], off
	s_mov_b32 m0, s39
	v_lshl_add_u64 v[210:211], v[216:217], 0, s[40:41]
	global_load_lds_dwordx4 v[210:211], off
	s_waitcnt vmcnt(10)
	s_barrier
	s_waitcnt lgkmcnt(0)
	v_mfma_f32_16x16x32_bf16 v[62:65], v[142:145], v[160:163], v[62:65]
	v_mfma_f32_16x16x32_bf16 v[58:61], v[152:155], v[160:163], v[58:61]
	v_mfma_f32_16x16x32_bf16 v[46:49], v[142:145], v[168:171], v[46:49]
	v_mfma_f32_16x16x32_bf16 v[42:45], v[152:155], v[168:171], v[42:45]
	v_mfma_f32_16x16x32_bf16 v[30:33], v[142:145], v[176:179], v[30:33]
	v_mfma_f32_16x16x32_bf16 v[26:29], v[152:155], v[176:179], v[26:29]
	v_mfma_f32_16x16x32_bf16 v[14:17], v[142:145], v[184:187], v[14:17]
	v_mfma_f32_16x16x32_bf16 v[10:13], v[152:155], v[184:187], v[10:13]
	v_mfma_f32_16x16x32_bf16 v[62:65], v[146:149], v[164:167], v[62:65]
	v_mfma_f32_16x16x32_bf16 v[58:61], v[156:159], v[164:167], v[58:61]
	v_mfma_f32_16x16x32_bf16 v[46:49], v[146:149], v[172:175], v[46:49]
	v_mfma_f32_16x16x32_bf16 v[42:45], v[156:159], v[172:175], v[42:45]
	v_mfma_f32_16x16x32_bf16 v[30:33], v[146:149], v[180:183], v[30:33]
	v_mfma_f32_16x16x32_bf16 v[26:29], v[156:159], v[180:183], v[26:29]
	v_mfma_f32_16x16x32_bf16 v[14:17], v[146:149], v[190:193], v[14:17]
	v_mfma_f32_16x16x32_bf16 v[10:13], v[156:159], v[190:193], v[10:13]
	s_barrier
	s_add_u32 s12, s12, 0x40080
	s_addc_u32 s13, s13, 0
	s_add_i32 s14, s14, s22
	s_mov_b32 m0, s14
	v_lshl_add_u64 v[142:143], s[12:13], 0, v[134:135]
	global_load_lds_dwordx4 v[142:143], off
	s_add_i32 m0, s14, 0x2000
	v_lshl_add_u64 v[142:143], s[12:13], 0, v[130:131]
	global_load_lds_dwordx4 v[142:143], off
	s_add_i32 s86, 0, 0x10000
	v_add_u32_e32 v0, s86, v150
	ds_read_b128 v[142:145], v0
	ds_read_b128 v[146:149], v0 offset:1024
	ds_read_b128 v[152:155], v0 offset:2048
	ds_read_b128 v[156:159], v0 offset:3072
	s_waitcnt vmcnt(6)
	s_barrier
	v_mfma_f32_16x16x32_bf16 v[54:57], v[194:197], v[160:163], v[54:57]
	v_mfma_f32_16x16x32_bf16 v[50:53], v[202:205], v[160:163], v[50:53]
	v_mfma_f32_16x16x32_bf16 v[38:41], v[194:197], v[168:171], v[38:41]
	v_mfma_f32_16x16x32_bf16 v[34:37], v[202:205], v[168:171], v[34:37]
	v_mfma_f32_16x16x32_bf16 v[22:25], v[194:197], v[176:179], v[22:25]
	v_mfma_f32_16x16x32_bf16 v[18:21], v[202:205], v[176:179], v[18:21]
	v_mfma_f32_16x16x32_bf16 v[6:9], v[194:197], v[184:187], v[6:9]
	v_mfma_f32_16x16x32_bf16 v[2:5], v[202:205], v[184:187], v[2:5]
	v_mfma_f32_16x16x32_bf16 v[54:57], v[198:201], v[164:167], v[54:57]
	v_mfma_f32_16x16x32_bf16 v[50:53], v[206:209], v[164:167], v[50:53]
	v_mfma_f32_16x16x32_bf16 v[38:41], v[198:201], v[172:175], v[38:41]
	v_mfma_f32_16x16x32_bf16 v[34:37], v[206:209], v[172:175], v[34:37]
	v_mfma_f32_16x16x32_bf16 v[22:25], v[198:201], v[180:183], v[22:25]
	v_mfma_f32_16x16x32_bf16 v[18:21], v[206:209], v[180:183], v[18:21]
	v_mfma_f32_16x16x32_bf16 v[6:9], v[198:201], v[190:193], v[6:9]
	v_mfma_f32_16x16x32_bf16 v[2:5], v[206:209], v[190:193], v[2:5]
	s_add_i32 s85, s85, 2
	s_add_u32 s4, s4, 0x100
	s_addc_u32 s5, s5, 0
	s_add_u32 s78, s78, 0x100
	s_addc_u32 s79, s79, 0
	s_cmp_gt_u32 s85, 13
	s_barrier
	s_cbranch_scc0 .LBB0_267
	s_waitcnt lgkmcnt(0)
	v_mov_b32_e32 v156, v252
	s_mov_b64 s[4:5], -1
	v_and_b32_e32 v154, 63, v156
	s_andn2_b64 vcc, exec, s[2:3]
	v_lshlrev_b32_e32 v142, 2, v154
	s_cbranch_vccnz .LBB0_270
	v_lshlrev_b32_e32 v155, 2, v154
	s_mov_b64 s[4:5], 0

.LBB0_837:
	s_ashr_i32 s15, s14, 31
	s_lshl_b64 s[78:79], s[14:15], 19
	s_add_u32 s84, s36, s78
	s_addc_u32 s85, s37, s79
	s_and_b64 s[4:5], s[4:5], exec
	s_cselect_b32 s15, s85, s91
	s_cselect_b32 s23, s84, s90
	s_add_u32 s34, s90, 0x100
	v_mov_b32_e32 v2, 0
	s_addc_u32 s75, s91, 0
	s_mov_b32 s78, -2
	s_waitcnt lgkmcnt(0)
	v_mov_b32_e32 v3, v2
	v_mov_b32_e32 v4, v2
	v_mov_b32_e32 v5, v2
	v_mov_b32_e32 v6, v2
	v_mov_b32_e32 v7, v2
	v_mov_b32_e32 v8, v2
	v_mov_b32_e32 v9, v2
	v_mov_b32_e32 v18, v2
	v_mov_b32_e32 v19, v2
	v_mov_b32_e32 v20, v2
	v_mov_b32_e32 v21, v2
	v_mov_b32_e32 v22, v2
	v_mov_b32_e32 v23, v2
	v_mov_b32_e32 v24, v2
	v_mov_b32_e32 v25, v2
	v_mov_b32_e32 v34, v2
	v_mov_b32_e32 v35, v2
	v_mov_b32_e32 v36, v2
	v_mov_b32_e32 v37, v2
	v_mov_b32_e32 v38, v2
	v_mov_b32_e32 v39, v2
	v_mov_b32_e32 v40, v2
	v_mov_b32_e32 v41, v2
	v_mov_b32_e32 v50, v2
	v_mov_b32_e32 v51, v2
	v_mov_b32_e32 v52, v2
	v_mov_b32_e32 v53, v2
	v_mov_b32_e32 v54, v2
	v_mov_b32_e32 v55, v2
	v_mov_b32_e32 v56, v2
	v_mov_b32_e32 v57, v2
	v_mov_b32_e32 v10, v2
	v_mov_b32_e32 v11, v2
	v_mov_b32_e32 v12, v2
	v_mov_b32_e32 v13, v2
	v_mov_b32_e32 v14, v2
	v_mov_b32_e32 v15, v2
	v_mov_b32_e32 v16, v2
	v_mov_b32_e32 v17, v2
	v_mov_b32_e32 v26, v2
	v_mov_b32_e32 v27, v2
	v_mov_b32_e32 v28, v2
	v_mov_b32_e32 v29, v2
	v_mov_b32_e32 v30, v2
	v_mov_b32_e32 v31, v2
	v_mov_b32_e32 v32, v2
	v_mov_b32_e32 v33, v2
	v_mov_b32_e32 v42, v2
	v_mov_b32_e32 v43, v2
	v_mov_b32_e32 v44, v2
	v_mov_b32_e32 v45, v2
	v_mov_b32_e32 v46, v2
	v_mov_b32_e32 v47, v2
	v_mov_b32_e32 v48, v2
	v_mov_b32_e32 v49, v2
	v_mov_b32_e32 v58, v2
	v_mov_b32_e32 v59, v2
	v_mov_b32_e32 v60, v2
	v_mov_b32_e32 v61, v2
	v_mov_b32_e32 v62, v2
	v_mov_b32_e32 v63, v2
	v_mov_b32_e32 v64, v2
	v_mov_b32_e32 v65, v2
	v_mov_b32_e32 v66, v2
	v_mov_b32_e32 v67, v2
	v_mov_b32_e32 v68, v2
	v_mov_b32_e32 v69, v2
	v_mov_b32_e32 v70, v2
	v_mov_b32_e32 v71, v2
	v_mov_b32_e32 v72, v2
	v_mov_b32_e32 v73, v2
	v_mov_b32_e32 v82, v2
	v_mov_b32_e32 v83, v2
	v_mov_b32_e32 v84, v2
	v_mov_b32_e32 v85, v2
	v_mov_b32_e32 v86, v2
	v_mov_b32_e32 v87, v2
	v_mov_b32_e32 v88, v2
	v_mov_b32_e32 v89, v2
	v_mov_b32_e32 v98, v2
	v_mov_b32_e32 v99, v2
	v_mov_b32_e32 v100, v2
	v_mov_b32_e32 v101, v2
	v_mov_b32_e32 v102, v2
	v_mov_b32_e32 v103, v2
	v_mov_b32_e32 v104, v2
	v_mov_b32_e32 v105, v2
	v_mov_b32_e32 v114, v2
	v_mov_b32_e32 v115, v2
	v_mov_b32_e32 v116, v2
	v_mov_b32_e32 v117, v2
	v_mov_b32_e32 v118, v2
	v_mov_b32_e32 v119, v2
	v_mov_b32_e32 v120, v2
	v_mov_b32_e32 v121, v2
	v_mov_b32_e32 v74, v2
	v_mov_b32_e32 v75, v2
	v_mov_b32_e32 v76, v2
	v_mov_b32_e32 v77, v2
	v_mov_b32_e32 v78, v2
	v_mov_b32_e32 v79, v2
	v_mov_b32_e32 v80, v2
	v_mov_b32_e32 v81, v2
	v_mov_b32_e32 v90, v2
	v_mov_b32_e32 v91, v2
	v_mov_b32_e32 v92, v2
	v_mov_b32_e32 v93, v2
	v_mov_b32_e32 v94, v2
	v_mov_b32_e32 v95, v2
	v_mov_b32_e32 v96, v2
	v_mov_b32_e32 v97, v2
	v_mov_b32_e32 v106, v2
	v_mov_b32_e32 v107, v2
	v_mov_b32_e32 v108, v2
	v_mov_b32_e32 v109, v2
	v_mov_b32_e32 v110, v2
	v_mov_b32_e32 v111, v2
	v_mov_b32_e32 v112, v2
	v_mov_b32_e32 v113, v2
	v_mov_b32_e32 v122, v2
	v_mov_b32_e32 v123, v2
	v_mov_b32_e32 v124, v2
	v_mov_b32_e32 v125, v2
	v_mov_b32_e32 v126, v2
	v_mov_b32_e32 v127, v2
	v_mov_b32_e32 v128, v2
	v_mov_b32_e32 v129, v2
	s_add_i32 s79, 0, 0x10000
	v_add_u32_e32 v142, s79, v212
	ds_read_b128 v[130:133], v142
	ds_read_b128 v[134:137], v142 offset:1024
	ds_read_b128 v[138:141], v142 offset:2048
	ds_read_b128 v[142:145], v142 offset:3072
.LBB0_838:
	s_add_u32 s4, s88, 0x100
	s_addc_u32 s5, s89, 0
	s_cmp_eq_u32 s78, 12
	s_cselect_b32 s93, s17, s5
	s_cselect_b32 s92, s16, s4
	s_cselect_b32 s91, s15, s75
	s_cselect_b32 s90, s23, s34
	v_lshl_add_u64 v[178:179], s[88:89], 0, v[196:197]
	s_add_i32 m0, s39, 0xc000
	ds_read_b128 v[146:149], v213
	ds_read_b128 v[150:153], v213 offset:1024
	ds_read_b128 v[154:157], v213 offset:2048
	ds_read_b128 v[158:161], v213 offset:3072
	ds_read_b128 v[162:165], v213 offset:4096
	ds_read_b128 v[166:169], v213 offset:5120
	ds_read_b128 v[170:173], v213 offset:6144
	ds_read_b128 v[174:177], v213 offset:7168
	global_load_lds_dwordx4 v[178:179], off
	s_add_i32 m0, s39, 0xe000
	v_lshl_add_u64 v[178:179], s[88:89], 0, v[198:199]
	global_load_lds_dwordx4 v[178:179], off
	s_waitcnt lgkmcnt(8)
	s_barrier
	s_waitcnt lgkmcnt(0)
	v_mfma_f32_16x16x32_bf16 v[126:129], v[130:133], v[146:149], v[126:129]
	v_mfma_f32_16x16x32_bf16 v[122:125], v[138:141], v[146:149], v[122:125]
	v_mfma_f32_16x16x32_bf16 v[110:113], v[130:133], v[154:157], v[110:113]
	v_mfma_f32_16x16x32_bf16 v[106:109], v[138:141], v[154:157], v[106:109]
	v_mfma_f32_16x16x32_bf16 v[94:97], v[130:133], v[162:165], v[94:97]
	v_mfma_f32_16x16x32_bf16 v[90:93], v[138:141], v[162:165], v[90:93]
	v_mfma_f32_16x16x32_bf16 v[78:81], v[130:133], v[170:173], v[78:81]
	v_mfma_f32_16x16x32_bf16 v[74:77], v[138:141], v[170:173], v[74:77]
	v_mfma_f32_16x16x32_bf16 v[126:129], v[134:137], v[150:153], v[126:129]
	v_mfma_f32_16x16x32_bf16 v[122:125], v[142:145], v[150:153], v[122:125]
	v_mfma_f32_16x16x32_bf16 v[110:113], v[134:137], v[158:161], v[110:113]
	v_mfma_f32_16x16x32_bf16 v[106:109], v[142:145], v[158:161], v[106:109]
	v_mfma_f32_16x16x32_bf16 v[94:97], v[134:137], v[166:169], v[94:97]
	v_mfma_f32_16x16x32_bf16 v[90:93], v[142:145], v[166:169], v[90:93]
	v_mfma_f32_16x16x32_bf16 v[78:81], v[134:137], v[174:177], v[78:81]
	v_mfma_f32_16x16x32_bf16 v[74:77], v[142:145], v[174:177], v[74:77]
	s_barrier
	s_add_i32 s87, 0, 0x14000
	v_add_u32_e32 v186, s87, v212
	s_add_i32 s79, s79, s38
	ds_read_b128 v[178:181], v186
	ds_read_b128 v[182:185], v186 offset:1024
	ds_read_b128 v[200:203], v186 offset:2048
	ds_read_b128 v[204:207], v186 offset:3072
	v_lshl_add_u64 v[186:187], s[90:91], 0, v[0:1]
	s_mov_b32 m0, s79
	v_lshl_add_u64 v[208:209], s[90:91], 0, v[194:195]
	global_load_lds_dwordx4 v[186:187], off
	s_add_i32 m0, s79, 0x2000
	s_nop 0
	global_load_lds_dwordx4 v[208:209], off
	s_barrier
	s_waitcnt lgkmcnt(0)
	v_mfma_f32_16x16x32_bf16 v[118:121], v[178:181], v[146:149], v[118:121]
	v_mfma_f32_16x16x32_bf16 v[114:117], v[200:203], v[146:149], v[114:117]
	v_mfma_f32_16x16x32_bf16 v[102:105], v[178:181], v[154:157], v[102:105]
	v_mfma_f32_16x16x32_bf16 v[98:101], v[200:203], v[154:157], v[98:101]
	v_mfma_f32_16x16x32_bf16 v[86:89], v[178:181], v[162:165], v[86:89]
	v_mfma_f32_16x16x32_bf16 v[82:85], v[200:203], v[162:165], v[82:85]
	v_mfma_f32_16x16x32_bf16 v[70:73], v[178:181], v[170:173], v[70:73]
	v_mfma_f32_16x16x32_bf16 v[66:69], v[200:203], v[170:173], v[66:69]
	v_mfma_f32_16x16x32_bf16 v[118:121], v[182:185], v[150:153], v[118:121]
	v_mfma_f32_16x16x32_bf16 v[114:117], v[204:207], v[150:153], v[114:117]
	v_mfma_f32_16x16x32_bf16 v[102:105], v[182:185], v[158:161], v[102:105]
	v_mfma_f32_16x16x32_bf16 v[98:101], v[204:207], v[158:161], v[98:101]
	v_mfma_f32_16x16x32_bf16 v[86:89], v[182:185], v[166:169], v[86:89]
	v_mfma_f32_16x16x32_bf16 v[82:85], v[204:207], v[166:169], v[82:85]
	v_mfma_f32_16x16x32_bf16 v[70:73], v[182:185], v[174:177], v[70:73]
	v_mfma_f32_16x16x32_bf16 v[66:69], v[204:207], v[174:177], v[66:69]
	s_mov_b32 m0, s39
	v_lshl_add_u64 v[210:211], s[92:93], 0, v[190:191]
	s_barrier
	ds_read_b128 v[146:149], v213 offset:16384
	ds_read_b128 v[150:153], v213 offset:17408
	ds_read_b128 v[154:157], v213 offset:18432
	ds_read_b128 v[158:161], v213 offset:19456
	ds_read_b128 v[162:165], v213 offset:20480
	ds_read_b128 v[166:169], v213 offset:21504
	ds_read_b128 v[170:173], v213 offset:22528
	ds_read_b128 v[174:177], v213 offset:23552
	global_load_lds_dwordx4 v[210:211], off
	s_mov_b32 m0, s42
	v_lshl_add_u64 v[214:215], s[92:93], 0, v[192:193]
	global_load_lds_dwordx4 v[214:215], off
	s_waitcnt vmcnt(10)
	s_barrier
	s_waitcnt lgkmcnt(0)
	v_mfma_f32_16x16x32_bf16 v[62:65], v[130:133], v[146:149], v[62:65]
	v_mfma_f32_16x16x32_bf16 v[58:61], v[138:141], v[146:149], v[58:61]
	v_mfma_f32_16x16x32_bf16 v[46:49], v[130:133], v[154:157], v[46:49]
	v_mfma_f32_16x16x32_bf16 v[42:45], v[138:141], v[154:157], v[42:45]
	v_mfma_f32_16x16x32_bf16 v[30:33], v[130:133], v[162:165], v[30:33]
	v_mfma_f32_16x16x32_bf16 v[26:29], v[138:141], v[162:165], v[26:29]
	v_mfma_f32_16x16x32_bf16 v[14:17], v[130:133], v[170:173], v[14:17]
	v_mfma_f32_16x16x32_bf16 v[10:13], v[138:141], v[170:173], v[10:13]
	v_mfma_f32_16x16x32_bf16 v[62:65], v[134:137], v[150:153], v[62:65]
	v_mfma_f32_16x16x32_bf16 v[58:61], v[142:145], v[150:153], v[58:61]
	v_mfma_f32_16x16x32_bf16 v[46:49], v[134:137], v[158:161], v[46:49]
	v_mfma_f32_16x16x32_bf16 v[42:45], v[142:145], v[158:161], v[42:45]
	v_mfma_f32_16x16x32_bf16 v[30:33], v[134:137], v[166:169], v[30:33]
	v_mfma_f32_16x16x32_bf16 v[26:29], v[142:145], v[166:169], v[26:29]
	v_mfma_f32_16x16x32_bf16 v[14:17], v[134:137], v[174:177], v[14:17]
	v_mfma_f32_16x16x32_bf16 v[10:13], v[142:145], v[174:177], v[10:13]
	s_barrier
	s_add_u32 s88, s90, 0x40000
	s_addc_u32 s89, s91, 0
	s_add_i32 s79, s87, s38
	s_mov_b32 m0, s79
	v_lshl_add_u64 v[130:131], s[88:89], 0, v[0:1]
	global_load_lds_dwordx4 v[130:131], off
	s_add_i32 m0, s79, 0x2000
	v_lshl_add_u64 v[130:131], s[88:89], 0, v[194:195]
	global_load_lds_dwordx4 v[130:131], off
	s_add_i32 s79, 0, 0x18000
	v_add_u32_e32 v142, s79, v212
	ds_read_b128 v[130:133], v142
	ds_read_b128 v[134:137], v142 offset:1024
	ds_read_b128 v[138:141], v142 offset:2048
	ds_read_b128 v[142:145], v142 offset:3072
	s_waitcnt vmcnt(6)
	s_barrier
	v_mfma_f32_16x16x32_bf16 v[54:57], v[178:181], v[146:149], v[54:57]
	v_mfma_f32_16x16x32_bf16 v[50:53], v[200:203], v[146:149], v[50:53]
	v_mfma_f32_16x16x32_bf16 v[38:41], v[178:181], v[154:157], v[38:41]
	v_mfma_f32_16x16x32_bf16 v[34:37], v[200:203], v[154:157], v[34:37]
	v_mfma_f32_16x16x32_bf16 v[22:25], v[178:181], v[162:165], v[22:25]
	v_mfma_f32_16x16x32_bf16 v[18:21], v[200:203], v[162:165], v[18:21]
	v_mfma_f32_16x16x32_bf16 v[6:9], v[178:181], v[170:173], v[6:9]
	v_mfma_f32_16x16x32_bf16 v[2:5], v[200:203], v[170:173], v[2:5]
	v_mfma_f32_16x16x32_bf16 v[54:57], v[182:185], v[150:153], v[54:57]
	v_mfma_f32_16x16x32_bf16 v[50:53], v[204:207], v[150:153], v[50:53]
	v_mfma_f32_16x16x32_bf16 v[38:41], v[182:185], v[158:161], v[38:41]
	v_mfma_f32_16x16x32_bf16 v[34:37], v[204:207], v[158:161], v[34:37]
	v_mfma_f32_16x16x32_bf16 v[22:25], v[182:185], v[166:169], v[22:25]
	v_mfma_f32_16x16x32_bf16 v[18:21], v[204:207], v[166:169], v[18:21]
	v_mfma_f32_16x16x32_bf16 v[6:9], v[182:185], v[174:177], v[6:9]
	v_mfma_f32_16x16x32_bf16 v[2:5], v[204:207], v[174:177], v[2:5]
	s_barrier
	s_add_u32 s88, s92, 0xc0000
	s_addc_u32 s89, s93, 0
	s_mov_b32 m0, s43
	v_lshl_add_u64 v[178:179], s[88:89], 0, v[190:191]
	ds_read_b128 v[146:149], v213 offset:32768
	ds_read_b128 v[150:153], v213 offset:33792
	ds_read_b128 v[154:157], v213 offset:34816
	ds_read_b128 v[158:161], v213 offset:35840
	ds_read_b128 v[162:165], v213 offset:36864
	ds_read_b128 v[166:169], v213 offset:37888
	ds_read_b128 v[170:173], v213 offset:38912
	ds_read_b128 v[174:177], v213 offset:39936
	global_load_lds_dwordx4 v[178:179], off
	s_mov_b32 m0, s44
	v_lshl_add_u64 v[178:179], s[88:89], 0, v[192:193]
	global_load_lds_dwordx4 v[178:179], off
	s_waitcnt lgkmcnt(8)
	s_barrier
	s_waitcnt lgkmcnt(0)
	v_mfma_f32_16x16x32_bf16 v[126:129], v[130:133], v[146:149], v[126:129]
	v_mfma_f32_16x16x32_bf16 v[122:125], v[138:141], v[146:149], v[122:125]
	v_mfma_f32_16x16x32_bf16 v[110:113], v[130:133], v[154:157], v[110:113]
	v_mfma_f32_16x16x32_bf16 v[106:109], v[138:141], v[154:157], v[106:109]
	v_mfma_f32_16x16x32_bf16 v[94:97], v[130:133], v[162:165], v[94:97]
	v_mfma_f32_16x16x32_bf16 v[90:93], v[138:141], v[162:165], v[90:93]
	v_mfma_f32_16x16x32_bf16 v[78:81], v[130:133], v[170:173], v[78:81]
	v_mfma_f32_16x16x32_bf16 v[74:77], v[138:141], v[170:173], v[74:77]
	v_mfma_f32_16x16x32_bf16 v[126:129], v[134:137], v[150:153], v[126:129]
	v_mfma_f32_16x16x32_bf16 v[122:125], v[142:145], v[150:153], v[122:125]
	v_mfma_f32_16x16x32_bf16 v[110:113], v[134:137], v[158:161], v[110:113]
	v_mfma_f32_16x16x32_bf16 v[106:109], v[142:145], v[158:161], v[106:109]
	v_mfma_f32_16x16x32_bf16 v[94:97], v[134:137], v[166:169], v[94:97]
	v_mfma_f32_16x16x32_bf16 v[90:93], v[142:145], v[166:169], v[90:93]
	v_mfma_f32_16x16x32_bf16 v[78:81], v[134:137], v[174:177], v[78:81]
	v_mfma_f32_16x16x32_bf16 v[74:77], v[142:145], v[174:177], v[74:77]
	s_barrier
	s_add_i32 s87, 0, 0x1c000
	s_add_i32 s79, s79, s38
	v_add_u32_e32 v204, s87, v212
	v_lshl_add_u64 v[186:187], v[186:187], 0, s[40:41]
	s_mov_b32 m0, s79
	ds_read_b128 v[178:181], v204
	ds_read_b128 v[182:185], v204 offset:1024
	ds_read_b128 v[200:203], v204 offset:2048
	ds_read_b128 v[204:207], v204 offset:3072
	global_load_lds_dwordx4 v[186:187], off
	s_add_i32 m0, s79, 0x2000
	v_lshl_add_u64 v[186:187], v[208:209], 0, s[40:41]
	global_load_lds_dwordx4 v[186:187], off
	s_barrier
	s_waitcnt lgkmcnt(0)
	v_mfma_f32_16x16x32_bf16 v[118:121], v[178:181], v[146:149], v[118:121]
	v_mfma_f32_16x16x32_bf16 v[114:117], v[200:203], v[146:149], v[114:117]
	v_mfma_f32_16x16x32_bf16 v[102:105], v[178:181], v[154:157], v[102:105]
	v_mfma_f32_16x16x32_bf16 v[98:101], v[200:203], v[154:157], v[98:101]
	v_mfma_f32_16x16x32_bf16 v[86:89], v[178:181], v[162:165], v[86:89]
	v_mfma_f32_16x16x32_bf16 v[82:85], v[200:203], v[162:165], v[82:85]
	v_mfma_f32_16x16x32_bf16 v[70:73], v[178:181], v[170:173], v[70:73]
	v_mfma_f32_16x16x32_bf16 v[66:69], v[200:203], v[170:173], v[66:69]
	v_mfma_f32_16x16x32_bf16 v[118:121], v[182:185], v[150:153], v[118:121]
	v_mfma_f32_16x16x32_bf16 v[114:117], v[204:207], v[150:153], v[114:117]
	v_mfma_f32_16x16x32_bf16 v[102:105], v[182:185], v[158:161], v[102:105]
	v_mfma_f32_16x16x32_bf16 v[98:101], v[204:207], v[158:161], v[98:101]
	v_mfma_f32_16x16x32_bf16 v[86:89], v[182:185], v[166:169], v[86:89]
	v_mfma_f32_16x16x32_bf16 v[82:85], v[204:207], v[166:169], v[82:85]
	v_mfma_f32_16x16x32_bf16 v[70:73], v[182:185], v[174:177], v[70:73]
	v_mfma_f32_16x16x32_bf16 v[66:69], v[204:207], v[174:177], v[66:69]
	s_mov_b32 m0, s60
	v_lshl_add_u64 v[186:187], v[210:211], 0, s[40:41]
	s_barrier
	ds_read_b128 v[146:149], v213 offset:49152
	ds_read_b128 v[150:153], v213 offset:50176
	ds_read_b128 v[154:157], v213 offset:51200
	ds_read_b128 v[158:161], v213 offset:52224
	ds_read_b128 v[162:165], v213 offset:53248
	ds_read_b128 v[166:169], v213 offset:54272
	ds_read_b128 v[170:173], v213 offset:55296
	ds_read_b128 v[174:177], v213 offset:56320
	global_load_lds_dwordx4 v[186:187], off
	s_mov_b32 m0, s61
	v_lshl_add_u64 v[186:187], v[214:215], 0, s[40:41]
	global_load_lds_dwordx4 v[186:187], off
	s_waitcnt vmcnt(10)
	s_barrier
	s_waitcnt lgkmcnt(0)
	v_mfma_f32_16x16x32_bf16 v[62:65], v[130:133], v[146:149], v[62:65]
	v_mfma_f32_16x16x32_bf16 v[58:61], v[138:141], v[146:149], v[58:61]
	v_mfma_f32_16x16x32_bf16 v[46:49], v[130:133], v[154:157], v[46:49]
	v_mfma_f32_16x16x32_bf16 v[42:45], v[138:141], v[154:157], v[42:45]
	v_mfma_f32_16x16x32_bf16 v[30:33], v[130:133], v[162:165], v[30:33]
	v_mfma_f32_16x16x32_bf16 v[26:29], v[138:141], v[162:165], v[26:29]
	v_mfma_f32_16x16x32_bf16 v[14:17], v[130:133], v[170:173], v[14:17]
	v_mfma_f32_16x16x32_bf16 v[10:13], v[138:141], v[170:173], v[10:13]
	v_mfma_f32_16x16x32_bf16 v[62:65], v[134:137], v[150:153], v[62:65]
	v_mfma_f32_16x16x32_bf16 v[58:61], v[142:145], v[150:153], v[58:61]
	v_mfma_f32_16x16x32_bf16 v[46:49], v[134:137], v[158:161], v[46:49]
	v_mfma_f32_16x16x32_bf16 v[42:45], v[142:145], v[158:161], v[42:45]
	v_mfma_f32_16x16x32_bf16 v[30:33], v[134:137], v[166:169], v[30:33]
	v_mfma_f32_16x16x32_bf16 v[26:29], v[142:145], v[166:169], v[26:29]
	v_mfma_f32_16x16x32_bf16 v[14:17], v[134:137], v[174:177], v[14:17]
	v_mfma_f32_16x16x32_bf16 v[10:13], v[142:145], v[174:177], v[10:13]
	s_barrier
	s_add_u32 s88, s90, 0x40080
	s_addc_u32 s89, s91, 0
	s_add_i32 s79, s87, s38
	s_mov_b32 m0, s79
	v_lshl_add_u64 v[130:131], s[88:89], 0, v[0:1]
	global_load_lds_dwordx4 v[130:131], off
	s_add_i32 m0, s79, 0x2000
	v_lshl_add_u64 v[130:131], s[88:89], 0, v[194:195]
	global_load_lds_dwordx4 v[130:131], off
	s_add_i32 s79, 0, 0x10000
	v_add_u32_e32 v142, s79, v212
	ds_read_b128 v[130:133], v142
	ds_read_b128 v[134:137], v142 offset:1024
	ds_read_b128 v[138:141], v142 offset:2048
	ds_read_b128 v[142:145], v142 offset:3072
	s_waitcnt vmcnt(6)
	s_barrier
	v_mfma_f32_16x16x32_bf16 v[54:57], v[178:181], v[146:149], v[54:57]
	v_mfma_f32_16x16x32_bf16 v[50:53], v[200:203], v[146:149], v[50:53]
	v_mfma_f32_16x16x32_bf16 v[38:41], v[178:181], v[154:157], v[38:41]
	v_mfma_f32_16x16x32_bf16 v[34:37], v[200:203], v[154:157], v[34:37]
	v_mfma_f32_16x16x32_bf16 v[22:25], v[178:181], v[162:165], v[22:25]
	v_mfma_f32_16x16x32_bf16 v[18:21], v[200:203], v[162:165], v[18:21]
	v_mfma_f32_16x16x32_bf16 v[6:9], v[178:181], v[170:173], v[6:9]
	v_mfma_f32_16x16x32_bf16 v[2:5], v[200:203], v[170:173], v[2:5]
	v_mfma_f32_16x16x32_bf16 v[54:57], v[182:185], v[150:153], v[54:57]
	v_mfma_f32_16x16x32_bf16 v[50:53], v[204:207], v[150:153], v[50:53]
	v_mfma_f32_16x16x32_bf16 v[38:41], v[182:185], v[158:161], v[38:41]
	v_mfma_f32_16x16x32_bf16 v[34:37], v[204:207], v[158:161], v[34:37]
	v_mfma_f32_16x16x32_bf16 v[22:25], v[182:185], v[166:169], v[22:25]
	v_mfma_f32_16x16x32_bf16 v[18:21], v[204:207], v[166:169], v[18:21]
	v_mfma_f32_16x16x32_bf16 v[6:9], v[182:185], v[174:177], v[6:9]
	v_mfma_f32_16x16x32_bf16 v[2:5], v[204:207], v[174:177], v[2:5]
	s_add_i32 s78, s78, 2
	s_add_u32 s34, s34, 0x100
	s_addc_u32 s75, s75, 0
	s_cmp_gt_u32 s78, 13
	s_mov_b64 s[88:89], s[4:5]
	s_barrier
	s_cbranch_scc0 .LBB0_838
	s_waitcnt lgkmcnt(0)
	s_lshl_b32 s4, s22, 8
	v_mov_b32_e32 v186, v252
	s_add_i32 s4, s4, s47
	s_nop 0
	v_and_or_b32 v202, v186, 15, s4
	s_lshl_b32 s4, s86, 8
	s_or_b32 s4, s4, s55
	v_lshrrev_b32_e32 v130, 1, v186
	v_and_or_b32 v200, v130, 24, s4
	v_ashrrev_i32_e32 v201, 31, v200
	v_ashrrev_i32_e32 v203, 31, v202
	v_lshl_add_u64 v[204:205], v[200:201], 2, s[6:7]
	v_lshlrev_b64 v[130:131], 12, v[202:203]
	v_lshl_add_u64 v[130:131], v[204:205], 0, v[130:131]
	global_load_dwordx4 v[216:219], v[130:131], off offset:16
	global_load_dwordx4 v[220:223], v[130:131], off
	global_load_dwordx4 v[178:181], v[130:131], off offset:528
	global_load_dwordx4 v[182:185], v[130:131], off offset:512
	v_or_b32_e32 v210, 16, v202
	v_ashrrev_i32_e32 v211, 31, v210
	v_lshlrev_b64 v[130:131], 12, v[210:211]
	v_or_b32_e32 v208, 32, v202
	v_lshl_add_u64 v[130:131], v[204:205], 0, v[130:131]
	v_ashrrev_i32_e32 v209, 31, v208
	global_load_dwordx4 v[170:173], v[130:131], off offset:16
	global_load_dwordx4 v[174:177], v[130:131], off
	global_load_dwordx4 v[162:165], v[130:131], off offset:528
	global_load_dwordx4 v[166:169], v[130:131], off offset:512
	v_lshlrev_b64 v[130:131], 12, v[208:209]
	v_or_b32_e32 v206, 48, v202
	v_lshl_add_u64 v[130:131], v[204:205], 0, v[130:131]
	v_ashrrev_i32_e32 v207, 31, v206
	global_load_dwordx4 v[154:157], v[130:131], off offset:16
	global_load_dwordx4 v[158:161], v[130:131], off
	global_load_dwordx4 v[138:141], v[130:131], off offset:528
	global_load_dwordx4 v[142:145], v[130:131], off offset:512
	v_lshlrev_b64 v[130:131], 12, v[206:207]
	v_lshl_add_u64 v[134:135], v[204:205], 0, v[130:131]
	global_load_dwordx4 v[146:149], v[134:135], off offset:16
	global_load_dwordx4 v[150:153], v[134:135], off
	global_load_dwordx4 v[130:133], v[134:135], off offset:528
	s_nop 0
	global_load_dwordx4 v[134:137], v[134:135], off offset:512
	v_and_b32_e32 v186, 63, v186
	v_lshlrev_b32_e32 v187, 2, v186
	v_xor_b32_e32 v215, 64, v187
	v_xor_b32_e32 v214, 0x80, v187
	v_cmp_gt_u32_e32 vcc, 16, v186
	v_lshlrev_b64 v[186:187], 10, v[202:203]
	v_lshl_add_u64 v[186:187], v[186:187], 0, v[200:201]
	s_lshl_b32 s4, s86, 2
	s_ashr_i32 s5, s4, 31
	s_waitcnt vmcnt(0)
	v_pk_add_f32 v[124:125], v[124:125], v[218:219]
	v_pk_add_f32 v[128:129], v[128:129], v[222:223]
	v_pk_add_f32 v[126:127], v[126:127], v[220:221]
	v_pk_mul_f32 v[218:219], v[128:129], v[128:129]
	v_pk_mul_f32 v[220:221], v[126:127], v[126:127]
	v_pk_add_f32 v[122:123], v[122:123], v[216:217]
	v_lshl_add_u64 v[216:217], v[186:187], 2, s[12:13]
	v_add_f32_e32 v220, v220, v221
	v_add_f32_e32 v218, v218, v219
	global_store_dwordx4 v[216:217], v[126:129], off
	global_store_dwordx4 v[216:217], v[122:125], off offset:16
	v_add_f32_e32 v222, v220, v218
	v_pk_mul_f32 v[220:221], v[122:123], v[122:123]
	v_cvt_pk_bf16_f32 v126, v126, v127
	v_cvt_pk_bf16_f32 v127, v128, v129
	v_cvt_pk_bf16_f32 v128, v122, v123
	v_cvt_pk_bf16_f32 v129, v124, v125
	v_lshl_add_u64 v[122:123], v[186:187], 1, s[8:9]
	v_pk_add_f32 v[120:121], v[120:121], v[184:185]
	v_pk_add_f32 v[118:119], v[118:119], v[182:183]
	v_pk_mul_f32 v[218:219], v[124:125], v[124:125]
	global_store_dwordx4 v[122:123], v[126:129], off
	v_pk_mul_f32 v[124:125], v[120:121], v[120:121]
	v_pk_add_f32 v[116:117], v[116:117], v[180:181]
	v_pk_mul_f32 v[126:127], v[118:119], v[118:119]
	v_pk_add_f32 v[114:115], v[114:115], v[178:179]
	v_add_f32_e32 v126, v126, v127
	v_add_f32_e32 v124, v124, v125
	v_add_f32_e32 v128, v126, v124
	v_pk_mul_f32 v[124:125], v[116:117], v[116:117]
	v_pk_mul_f32 v[126:127], v[114:115], v[114:115]
	v_add_f32_e32 v220, v220, v221
	v_add_f32_e32 v218, v218, v219
	v_add_f32_e32 v126, v126, v127
	v_add_f32_e32 v124, v124, v125
	v_add_f32_e32 v218, v220, v218
	v_add_f32_e32 v124, v126, v124
	v_add_f32_e32 v218, v222, v218
	v_add_f32_e32 v124, v128, v124
	v_add_f32_e32 v124, v218, v124
	global_store_dwordx4 v[216:217], v[118:121], off offset:512
	global_store_dwordx4 v[216:217], v[114:117], off offset:528
	s_nop 0
	v_cvt_pk_bf16_f32 v118, v118, v119
	v_cvt_pk_bf16_f32 v119, v120, v121
	v_cvt_pk_bf16_f32 v120, v114, v115
	ds_bpermute_b32 v114, v215, v124
	v_cvt_pk_bf16_f32 v121, v116, v117
	global_store_dwordx4 v[122:123], v[118:121], off offset:256
	s_waitcnt lgkmcnt(0)
	v_add_f32_e32 v114, v124, v114
	ds_bpermute_b32 v115, v214, v114
	s_and_saveexec_b64 s[22:23], vcc
	s_cbranch_execz .LBB0_841
	v_lshlrev_b64 v[116:117], 6, v[202:203]
	v_lshl_add_u64 v[116:117], s[10:11], 0, v[116:117]
	v_lshl_add_u64 v[116:117], s[4:5], 2, v[116:117]
	s_lshl_b32 s34, s45, 2
	v_lshl_add_u64 v[116:117], v[116:117], 0, s[34:35]
	s_waitcnt lgkmcnt(0)
	v_add_f32_e32 v114, v114, v115
	global_store_dword v[116:117], v114, off

.LBB0_918:
	s_ashr_i32 s17, s16, 31
	s_lshl_b64 s[22:23], s[16:17], 19
	v_mov_b64_e32 v[2:3], 0xb00
	s_add_u32 s84, s8, s22
	v_cmp_lt_i64_e32 vcc, s[28:29], v[2:3]
	s_addc_u32 s85, s9, s23
	s_and_b64 s[22:23], vcc, exec
	s_cselect_b32 s17, s85, s7
	s_cselect_b32 s22, s84, s6
	s_ashr_i32 s15, s14, 31
	s_lshl_b64 s[28:29], s[14:15], 19
	s_add_u32 s86, s37, s28
	s_addc_u32 s87, s38, s29
	s_and_b64 s[28:29], vcc, exec
	s_cselect_b32 s15, s87, s89
	s_cselect_b32 s23, s86, s88
	s_add_u32 s28, s88, 0x100
	v_mov_b32_e32 v70, 0
	s_addc_u32 s29, s89, 0
	s_mov_b32 s45, -2
	v_mov_b32_e32 v71, v70
	v_mov_b32_e32 v72, v70
	v_mov_b32_e32 v73, v70
	v_mov_b32_e32 v74, v70
	v_mov_b32_e32 v75, v70
	v_mov_b32_e32 v76, v70
	v_mov_b32_e32 v77, v70
	v_mov_b32_e32 v66, v70
	v_mov_b32_e32 v67, v70
	v_mov_b32_e32 v68, v70
	v_mov_b32_e32 v69, v70
	v_mov_b32_e32 v78, v70
	v_mov_b32_e32 v79, v70
	v_mov_b32_e32 v80, v70
	v_mov_b32_e32 v81, v70
	v_mov_b32_e32 v94, v70
	v_mov_b32_e32 v95, v70
	v_mov_b32_e32 v96, v70
	v_mov_b32_e32 v97, v70
	v_mov_b32_e32 v90, v70
	v_mov_b32_e32 v91, v70
	v_mov_b32_e32 v92, v70
	v_mov_b32_e32 v93, v70
	v_mov_b32_e32 v82, v70
	v_mov_b32_e32 v83, v70
	v_mov_b32_e32 v84, v70
	v_mov_b32_e32 v85, v70
	v_mov_b32_e32 v86, v70
	v_mov_b32_e32 v87, v70
	v_mov_b32_e32 v88, v70
	v_mov_b32_e32 v89, v70
	v_mov_b32_e32 v10, v70
	v_mov_b32_e32 v11, v70
	v_mov_b32_e32 v12, v70
	v_mov_b32_e32 v13, v70
	v_mov_b32_e32 v14, v70
	v_mov_b32_e32 v15, v70
	v_mov_b32_e32 v16, v70
	v_mov_b32_e32 v17, v70
	v_mov_b32_e32 v6, v70
	v_mov_b32_e32 v7, v70
	v_mov_b32_e32 v8, v70
	v_mov_b32_e32 v9, v70
	v_mov_b32_e32 v2, v70
	v_mov_b32_e32 v3, v70
	v_mov_b32_e32 v4, v70
	v_mov_b32_e32 v5, v70
	v_mov_b32_e32 v26, v70
	v_mov_b32_e32 v27, v70
	v_mov_b32_e32 v28, v70
	v_mov_b32_e32 v29, v70
	v_mov_b32_e32 v30, v70
	v_mov_b32_e32 v31, v70
	v_mov_b32_e32 v32, v70
	v_mov_b32_e32 v33, v70
	v_mov_b32_e32 v22, v70
	v_mov_b32_e32 v23, v70
	v_mov_b32_e32 v24, v70
	v_mov_b32_e32 v25, v70
	v_mov_b32_e32 v18, v70
	v_mov_b32_e32 v19, v70
	v_mov_b32_e32 v20, v70
	v_mov_b32_e32 v21, v70
	v_mov_b32_e32 v34, v70
	v_mov_b32_e32 v35, v70
	v_mov_b32_e32 v36, v70
	v_mov_b32_e32 v37, v70
	v_mov_b32_e32 v38, v70
	v_mov_b32_e32 v39, v70
	v_mov_b32_e32 v40, v70
	v_mov_b32_e32 v41, v70
	v_mov_b32_e32 v46, v70
	v_mov_b32_e32 v47, v70
	v_mov_b32_e32 v48, v70
	v_mov_b32_e32 v49, v70
	v_mov_b32_e32 v50, v70
	v_mov_b32_e32 v51, v70
	v_mov_b32_e32 v52, v70
	v_mov_b32_e32 v53, v70
	v_mov_b32_e32 v42, v70
	v_mov_b32_e32 v43, v70
	v_mov_b32_e32 v44, v70
	v_mov_b32_e32 v45, v70
	v_mov_b32_e32 v54, v70
	v_mov_b32_e32 v55, v70
	v_mov_b32_e32 v56, v70
	v_mov_b32_e32 v57, v70
	v_mov_b32_e32 v58, v70
	v_mov_b32_e32 v59, v70
	v_mov_b32_e32 v60, v70
	v_mov_b32_e32 v61, v70
	v_mov_b32_e32 v62, v70
	v_mov_b32_e32 v63, v70
	v_mov_b32_e32 v64, v70
	v_mov_b32_e32 v65, v70
	v_mov_b32_e32 v98, v70
	v_mov_b32_e32 v99, v70
	v_mov_b32_e32 v100, v70
	v_mov_b32_e32 v101, v70
	v_mov_b32_e32 v102, v70
	v_mov_b32_e32 v103, v70
	v_mov_b32_e32 v104, v70
	v_mov_b32_e32 v105, v70
	v_mov_b32_e32 v106, v70
	v_mov_b32_e32 v107, v70
	v_mov_b32_e32 v108, v70
	v_mov_b32_e32 v109, v70
	v_mov_b32_e32 v118, v70
	v_mov_b32_e32 v119, v70
	v_mov_b32_e32 v120, v70
	v_mov_b32_e32 v121, v70
	v_mov_b32_e32 v110, v70
	v_mov_b32_e32 v111, v70
	v_mov_b32_e32 v112, v70
	v_mov_b32_e32 v113, v70
	v_mov_b32_e32 v114, v70
	v_mov_b32_e32 v115, v70
	v_mov_b32_e32 v116, v70
	v_mov_b32_e32 v117, v70
	v_mov_b32_e32 v122, v70
	v_mov_b32_e32 v123, v70
	v_mov_b32_e32 v124, v70
	v_mov_b32_e32 v125, v70
	v_mov_b32_e32 v126, v70
	v_mov_b32_e32 v127, v70
	v_mov_b32_e32 v128, v70
	v_mov_b32_e32 v129, v70
	s_add_i32 vcc_lo, 0, 0x10000
	v_add_u32_e32 v0, vcc_lo, v254
	ds_read_b128 v[130:133], v0
	ds_read_b128 v[134:137], v0 offset:1024
	ds_read_b128 v[138:141], v0 offset:2048
	ds_read_b128 v[142:145], v0 offset:3072
.LBB0_919:
	s_add_u32 s88, s6, 0x100
	s_addc_u32 s89, s7, 0
	s_cmp_eq_u32 s45, 12
	s_cselect_b32 s93, s17, s89
	s_cselect_b32 s92, s22, s88
	s_cselect_b32 s91, s15, s29
	s_cselect_b32 s90, s23, s28
	v_lshl_add_u64 v[154:155], s[6:7], 0, v[164:165]
	s_add_i32 m0, s43, 0xc000
	ds_read_b128 v[146:149], v253
	ds_read_b128 v[150:153], v253 offset:1024
	ds_read_b128 v[168:171], v253 offset:2048
	ds_read_b128 v[172:175], v253 offset:3072
	ds_read_b128 v[176:179], v253 offset:4096
	ds_read_b128 v[180:183], v253 offset:5120
	ds_read_b128 v[184:187], v253 offset:6144
	ds_read_b128 v[190:193], v253 offset:7168
	global_load_lds_dwordx4 v[154:155], off
	s_add_i32 m0, s43, 0xe000
	v_lshl_add_u64 v[154:155], s[6:7], 0, v[166:167]
	global_load_lds_dwordx4 v[154:155], off
	s_waitcnt lgkmcnt(8)
	s_barrier
	s_waitcnt lgkmcnt(0)
	v_mfma_f32_16x16x32_bf16 v[126:129], v[130:133], v[146:149], v[126:129]
	v_mfma_f32_16x16x32_bf16 v[70:73], v[138:141], v[146:149], v[70:73]
	v_mfma_f32_16x16x32_bf16 v[122:125], v[130:133], v[168:171], v[122:125]
	v_mfma_f32_16x16x32_bf16 v[74:77], v[138:141], v[168:171], v[74:77]
	v_mfma_f32_16x16x32_bf16 v[114:117], v[130:133], v[176:179], v[114:117]
	v_mfma_f32_16x16x32_bf16 v[66:69], v[138:141], v[176:179], v[66:69]
	v_mfma_f32_16x16x32_bf16 v[110:113], v[130:133], v[184:187], v[110:113]
	v_mfma_f32_16x16x32_bf16 v[78:81], v[138:141], v[184:187], v[78:81]
	v_mfma_f32_16x16x32_bf16 v[126:129], v[134:137], v[150:153], v[126:129]
	v_mfma_f32_16x16x32_bf16 v[70:73], v[142:145], v[150:153], v[70:73]
	v_mfma_f32_16x16x32_bf16 v[122:125], v[134:137], v[172:175], v[122:125]
	v_mfma_f32_16x16x32_bf16 v[74:77], v[142:145], v[172:175], v[74:77]
	v_mfma_f32_16x16x32_bf16 v[114:117], v[134:137], v[180:183], v[114:117]
	v_mfma_f32_16x16x32_bf16 v[66:69], v[142:145], v[180:183], v[66:69]
	v_mfma_f32_16x16x32_bf16 v[110:113], v[134:137], v[190:193], v[110:113]
	v_mfma_f32_16x16x32_bf16 v[78:81], v[142:145], v[190:193], v[78:81]
	s_barrier
	s_add_i32 vcc_hi, 0, 0x14000
	s_add_i32 s6, vcc_lo, s39
	v_add_u32_e32 v0, vcc_hi, v254
	v_lshl_add_u64 v[154:155], s[90:91], 0, v[160:161]
	s_mov_b32 m0, s6
	ds_read_b128 v[194:197], v0
	ds_read_b128 v[198:201], v0 offset:1024
	ds_read_b128 v[202:205], v0 offset:2048
	ds_read_b128 v[206:209], v0 offset:3072
	global_load_lds_dwordx4 v[154:155], off
	s_add_i32 m0, s6, 0x2000
	v_lshl_add_u64 v[210:211], s[90:91], 0, v[156:157]
	global_load_lds_dwordx4 v[210:211], off
	s_barrier
	s_waitcnt lgkmcnt(0)
	v_mfma_f32_16x16x32_bf16 v[118:121], v[194:197], v[146:149], v[118:121]
	v_mfma_f32_16x16x32_bf16 v[94:97], v[202:205], v[146:149], v[94:97]
	v_mfma_f32_16x16x32_bf16 v[106:109], v[194:197], v[168:171], v[106:109]
	v_mfma_f32_16x16x32_bf16 v[90:93], v[202:205], v[168:171], v[90:93]
	v_mfma_f32_16x16x32_bf16 v[102:105], v[194:197], v[176:179], v[102:105]
	v_mfma_f32_16x16x32_bf16 v[82:85], v[202:205], v[176:179], v[82:85]
	v_mfma_f32_16x16x32_bf16 v[98:101], v[194:197], v[184:187], v[98:101]
	v_mfma_f32_16x16x32_bf16 v[86:89], v[202:205], v[184:187], v[86:89]
	v_mfma_f32_16x16x32_bf16 v[118:121], v[198:201], v[150:153], v[118:121]
	v_mfma_f32_16x16x32_bf16 v[94:97], v[206:209], v[150:153], v[94:97]
	v_mfma_f32_16x16x32_bf16 v[106:109], v[198:201], v[172:175], v[106:109]
	v_mfma_f32_16x16x32_bf16 v[90:93], v[206:209], v[172:175], v[90:93]
	v_mfma_f32_16x16x32_bf16 v[102:105], v[198:201], v[180:183], v[102:105]
	v_mfma_f32_16x16x32_bf16 v[82:85], v[206:209], v[180:183], v[82:85]
	v_mfma_f32_16x16x32_bf16 v[98:101], v[198:201], v[190:193], v[98:101]
	v_mfma_f32_16x16x32_bf16 v[86:89], v[206:209], v[190:193], v[86:89]
	s_mov_b32 m0, s43
	v_lshl_add_u64 v[212:213], s[92:93], 0, v[162:163]
	s_barrier
	ds_read_b128 v[146:149], v253 offset:16384
	ds_read_b128 v[150:153], v253 offset:17408
	ds_read_b128 v[168:171], v253 offset:18432
	ds_read_b128 v[172:175], v253 offset:19456
	ds_read_b128 v[176:179], v253 offset:20480
	ds_read_b128 v[180:183], v253 offset:21504
	ds_read_b128 v[184:187], v253 offset:22528
	ds_read_b128 v[190:193], v253 offset:23552
	global_load_lds_dwordx4 v[212:213], off
	s_mov_b32 m0, s60
	v_lshl_add_u64 v[214:215], s[92:93], 0, v[158:159]
	global_load_lds_dwordx4 v[214:215], off
	s_waitcnt vmcnt(10)
	s_barrier
	s_waitcnt lgkmcnt(0)
	v_mfma_f32_16x16x32_bf16 v[62:65], v[130:133], v[146:149], v[62:65]
	v_mfma_f32_16x16x32_bf16 v[10:13], v[138:141], v[146:149], v[10:13]
	v_mfma_f32_16x16x32_bf16 v[58:61], v[130:133], v[168:171], v[58:61]
	v_mfma_f32_16x16x32_bf16 v[14:17], v[138:141], v[168:171], v[14:17]
	v_mfma_f32_16x16x32_bf16 v[54:57], v[130:133], v[176:179], v[54:57]
	v_mfma_f32_16x16x32_bf16 v[6:9], v[138:141], v[176:179], v[6:9]
	v_mfma_f32_16x16x32_bf16 v[42:45], v[130:133], v[184:187], v[42:45]
	v_mfma_f32_16x16x32_bf16 v[2:5], v[138:141], v[184:187], v[2:5]
	v_mfma_f32_16x16x32_bf16 v[62:65], v[134:137], v[150:153], v[62:65]
	v_mfma_f32_16x16x32_bf16 v[10:13], v[142:145], v[150:153], v[10:13]
	v_mfma_f32_16x16x32_bf16 v[58:61], v[134:137], v[172:175], v[58:61]
	v_mfma_f32_16x16x32_bf16 v[14:17], v[142:145], v[172:175], v[14:17]
	v_mfma_f32_16x16x32_bf16 v[54:57], v[134:137], v[180:183], v[54:57]
	v_mfma_f32_16x16x32_bf16 v[6:9], v[142:145], v[180:183], v[6:9]
	v_mfma_f32_16x16x32_bf16 v[42:45], v[134:137], v[190:193], v[42:45]
	v_mfma_f32_16x16x32_bf16 v[2:5], v[142:145], v[190:193], v[2:5]
	s_barrier
	s_add_u32 s6, s90, 0x40000
	s_addc_u32 s7, s91, 0
	s_add_i32 vcc_lo, vcc_hi, s39
	s_mov_b32 m0, vcc_lo
	v_lshl_add_u64 v[130:131], s[6:7], 0, v[160:161]
	global_load_lds_dwordx4 v[130:131], off
	s_add_i32 m0, vcc_lo, 0x2000
	v_lshl_add_u64 v[130:131], s[6:7], 0, v[156:157]
	global_load_lds_dwordx4 v[130:131], off
	s_add_i32 vcc_lo, 0, 0x18000
	v_add_u32_e32 v0, vcc_lo, v254
	ds_read_b128 v[130:133], v0
	ds_read_b128 v[134:137], v0 offset:1024
	ds_read_b128 v[138:141], v0 offset:2048
	ds_read_b128 v[142:145], v0 offset:3072
	s_waitcnt vmcnt(6)
	s_barrier
	v_mfma_f32_16x16x32_bf16 v[50:53], v[194:197], v[146:149], v[50:53]
	v_mfma_f32_16x16x32_bf16 v[26:29], v[202:205], v[146:149], v[26:29]
	v_mfma_f32_16x16x32_bf16 v[46:49], v[194:197], v[168:171], v[46:49]
	v_mfma_f32_16x16x32_bf16 v[30:33], v[202:205], v[168:171], v[30:33]
	v_mfma_f32_16x16x32_bf16 v[38:41], v[194:197], v[176:179], v[38:41]
	v_mfma_f32_16x16x32_bf16 v[22:25], v[202:205], v[176:179], v[22:25]
	v_mfma_f32_16x16x32_bf16 v[34:37], v[194:197], v[184:187], v[34:37]
	v_mfma_f32_16x16x32_bf16 v[18:21], v[202:205], v[184:187], v[18:21]
	v_mfma_f32_16x16x32_bf16 v[50:53], v[198:201], v[150:153], v[50:53]
	v_mfma_f32_16x16x32_bf16 v[26:29], v[206:209], v[150:153], v[26:29]
	v_mfma_f32_16x16x32_bf16 v[46:49], v[198:201], v[172:175], v[46:49]
	v_mfma_f32_16x16x32_bf16 v[30:33], v[206:209], v[172:175], v[30:33]
	v_mfma_f32_16x16x32_bf16 v[38:41], v[198:201], v[180:183], v[38:41]
	v_mfma_f32_16x16x32_bf16 v[22:25], v[206:209], v[180:183], v[22:25]
	v_mfma_f32_16x16x32_bf16 v[34:37], v[198:201], v[190:193], v[34:37]
	v_mfma_f32_16x16x32_bf16 v[18:21], v[206:209], v[190:193], v[18:21]
	s_barrier
	s_add_u32 s6, s92, 0x40000
	s_addc_u32 s7, s93, 0
	s_mov_b32 m0, s61
	v_lshl_add_u64 v[194:195], s[6:7], 0, v[162:163]
	ds_read_b128 v[146:149], v253 offset:32768
	ds_read_b128 v[150:153], v253 offset:33792
	ds_read_b128 v[168:171], v253 offset:34816
	ds_read_b128 v[172:175], v253 offset:35840
	ds_read_b128 v[176:179], v253 offset:36864
	ds_read_b128 v[180:183], v253 offset:37888
	ds_read_b128 v[184:187], v253 offset:38912
	ds_read_b128 v[190:193], v253 offset:39936
	global_load_lds_dwordx4 v[194:195], off
	s_mov_b32 m0, s72
	v_lshl_add_u64 v[194:195], s[6:7], 0, v[158:159]
	global_load_lds_dwordx4 v[194:195], off
	s_waitcnt lgkmcnt(8)
	s_barrier
	s_waitcnt lgkmcnt(0)
	v_mfma_f32_16x16x32_bf16 v[126:129], v[130:133], v[146:149], v[126:129]
	v_mfma_f32_16x16x32_bf16 v[70:73], v[138:141], v[146:149], v[70:73]
	v_mfma_f32_16x16x32_bf16 v[122:125], v[130:133], v[168:171], v[122:125]
	v_mfma_f32_16x16x32_bf16 v[74:77], v[138:141], v[168:171], v[74:77]
	v_mfma_f32_16x16x32_bf16 v[114:117], v[130:133], v[176:179], v[114:117]
	v_mfma_f32_16x16x32_bf16 v[66:69], v[138:141], v[176:179], v[66:69]
	v_mfma_f32_16x16x32_bf16 v[110:113], v[130:133], v[184:187], v[110:113]
	v_mfma_f32_16x16x32_bf16 v[78:81], v[138:141], v[184:187], v[78:81]
	v_mfma_f32_16x16x32_bf16 v[126:129], v[134:137], v[150:153], v[126:129]
	v_mfma_f32_16x16x32_bf16 v[70:73], v[142:145], v[150:153], v[70:73]
	v_mfma_f32_16x16x32_bf16 v[122:125], v[134:137], v[172:175], v[122:125]
	v_mfma_f32_16x16x32_bf16 v[74:77], v[142:145], v[172:175], v[74:77]
	v_mfma_f32_16x16x32_bf16 v[114:117], v[134:137], v[180:183], v[114:117]
	v_mfma_f32_16x16x32_bf16 v[66:69], v[142:145], v[180:183], v[66:69]
	v_mfma_f32_16x16x32_bf16 v[110:113], v[134:137], v[190:193], v[110:113]
	v_mfma_f32_16x16x32_bf16 v[78:81], v[142:145], v[190:193], v[78:81]
	s_barrier
	s_add_i32 s92, 0, 0x1c000
	s_add_i32 s6, vcc_lo, s39
	v_add_u32_e32 v0, s92, v254
	v_lshl_add_u64 v[154:155], v[154:155], 0, s[40:41]
	s_mov_b32 m0, s6
	ds_read_b128 v[194:197], v0
	ds_read_b128 v[198:201], v0 offset:1024
	ds_read_b128 v[202:205], v0 offset:2048
	ds_read_b128 v[206:209], v0 offset:3072
	global_load_lds_dwordx4 v[154:155], off
	s_add_i32 m0, s6, 0x2000
	v_lshl_add_u64 v[154:155], v[210:211], 0, s[40:41]
	global_load_lds_dwordx4 v[154:155], off
	s_barrier
	s_waitcnt lgkmcnt(0)
	v_mfma_f32_16x16x32_bf16 v[118:121], v[194:197], v[146:149], v[118:121]
	v_mfma_f32_16x16x32_bf16 v[94:97], v[202:205], v[146:149], v[94:97]
	v_mfma_f32_16x16x32_bf16 v[106:109], v[194:197], v[168:171], v[106:109]
	v_mfma_f32_16x16x32_bf16 v[90:93], v[202:205], v[168:171], v[90:93]
	v_mfma_f32_16x16x32_bf16 v[102:105], v[194:197], v[176:179], v[102:105]
	v_mfma_f32_16x16x32_bf16 v[82:85], v[202:205], v[176:179], v[82:85]
	v_mfma_f32_16x16x32_bf16 v[98:101], v[194:197], v[184:187], v[98:101]
	v_mfma_f32_16x16x32_bf16 v[86:89], v[202:205], v[184:187], v[86:89]
	v_mfma_f32_16x16x32_bf16 v[118:121], v[198:201], v[150:153], v[118:121]
	v_mfma_f32_16x16x32_bf16 v[94:97], v[206:209], v[150:153], v[94:97]
	v_mfma_f32_16x16x32_bf16 v[106:109], v[198:201], v[172:175], v[106:109]
	v_mfma_f32_16x16x32_bf16 v[90:93], v[206:209], v[172:175], v[90:93]
	v_mfma_f32_16x16x32_bf16 v[102:105], v[198:201], v[180:183], v[102:105]
	v_mfma_f32_16x16x32_bf16 v[82:85], v[206:209], v[180:183], v[82:85]
	v_mfma_f32_16x16x32_bf16 v[98:101], v[198:201], v[190:193], v[98:101]
	v_mfma_f32_16x16x32_bf16 v[86:89], v[206:209], v[190:193], v[86:89]
	s_mov_b32 m0, s95
	v_lshl_add_u64 v[154:155], v[212:213], 0, s[40:41]
	s_barrier
	ds_read_b128 v[146:149], v253 offset:49152
	ds_read_b128 v[150:153], v253 offset:50176
	ds_read_b128 v[168:171], v253 offset:51200
	ds_read_b128 v[172:175], v253 offset:52224
	ds_read_b128 v[176:179], v253 offset:53248
	ds_read_b128 v[180:183], v253 offset:54272
	ds_read_b128 v[184:187], v253 offset:55296
	ds_read_b128 v[190:193], v253 offset:56320
	global_load_lds_dwordx4 v[154:155], off
	s_mov_b32 m0, s96
	v_lshl_add_u64 v[154:155], v[214:215], 0, s[40:41]
	global_load_lds_dwordx4 v[154:155], off
	s_waitcnt vmcnt(10)
	s_barrier
	s_waitcnt lgkmcnt(0)
	v_mfma_f32_16x16x32_bf16 v[62:65], v[130:133], v[146:149], v[62:65]
	v_mfma_f32_16x16x32_bf16 v[10:13], v[138:141], v[146:149], v[10:13]
	v_mfma_f32_16x16x32_bf16 v[58:61], v[130:133], v[168:171], v[58:61]
	v_mfma_f32_16x16x32_bf16 v[14:17], v[138:141], v[168:171], v[14:17]
	v_mfma_f32_16x16x32_bf16 v[54:57], v[130:133], v[176:179], v[54:57]
	v_mfma_f32_16x16x32_bf16 v[6:9], v[138:141], v[176:179], v[6:9]
	v_mfma_f32_16x16x32_bf16 v[42:45], v[130:133], v[184:187], v[42:45]
	v_mfma_f32_16x16x32_bf16 v[2:5], v[138:141], v[184:187], v[2:5]
	v_mfma_f32_16x16x32_bf16 v[62:65], v[134:137], v[150:153], v[62:65]
	v_mfma_f32_16x16x32_bf16 v[10:13], v[142:145], v[150:153], v[10:13]
	v_mfma_f32_16x16x32_bf16 v[58:61], v[134:137], v[172:175], v[58:61]
	v_mfma_f32_16x16x32_bf16 v[14:17], v[142:145], v[172:175], v[14:17]
	v_mfma_f32_16x16x32_bf16 v[54:57], v[134:137], v[180:183], v[54:57]
	v_mfma_f32_16x16x32_bf16 v[6:9], v[142:145], v[180:183], v[6:9]
	v_mfma_f32_16x16x32_bf16 v[42:45], v[134:137], v[190:193], v[42:45]
	v_mfma_f32_16x16x32_bf16 v[2:5], v[142:145], v[190:193], v[2:5]
	s_barrier
	s_add_u32 s6, s90, 0x40080
	s_addc_u32 s7, s91, 0
	s_add_i32 s90, s92, s39
	s_mov_b32 m0, s90
	v_lshl_add_u64 v[130:131], s[6:7], 0, v[160:161]
	global_load_lds_dwordx4 v[130:131], off
	s_add_i32 m0, s90, 0x2000
	v_lshl_add_u64 v[130:131], s[6:7], 0, v[156:157]
	global_load_lds_dwordx4 v[130:131], off
	s_add_i32 vcc_lo, 0, 0x10000
	v_add_u32_e32 v0, vcc_lo, v254
	ds_read_b128 v[130:133], v0
	ds_read_b128 v[134:137], v0 offset:1024
	ds_read_b128 v[138:141], v0 offset:2048
	ds_read_b128 v[142:145], v0 offset:3072
	s_waitcnt vmcnt(6)
	s_barrier
	v_mfma_f32_16x16x32_bf16 v[50:53], v[194:197], v[146:149], v[50:53]
	v_mfma_f32_16x16x32_bf16 v[26:29], v[202:205], v[146:149], v[26:29]
	v_mfma_f32_16x16x32_bf16 v[46:49], v[194:197], v[168:171], v[46:49]
	v_mfma_f32_16x16x32_bf16 v[30:33], v[202:205], v[168:171], v[30:33]
	v_mfma_f32_16x16x32_bf16 v[38:41], v[194:197], v[176:179], v[38:41]
	v_mfma_f32_16x16x32_bf16 v[22:25], v[202:205], v[176:179], v[22:25]
	v_mfma_f32_16x16x32_bf16 v[34:37], v[194:197], v[184:187], v[34:37]
	v_mfma_f32_16x16x32_bf16 v[18:21], v[202:205], v[184:187], v[18:21]
	v_mfma_f32_16x16x32_bf16 v[50:53], v[198:201], v[150:153], v[50:53]
	v_mfma_f32_16x16x32_bf16 v[26:29], v[206:209], v[150:153], v[26:29]
	v_mfma_f32_16x16x32_bf16 v[46:49], v[198:201], v[172:175], v[46:49]
	v_mfma_f32_16x16x32_bf16 v[30:33], v[206:209], v[172:175], v[30:33]
	v_mfma_f32_16x16x32_bf16 v[38:41], v[198:201], v[180:183], v[38:41]
	v_mfma_f32_16x16x32_bf16 v[22:25], v[206:209], v[180:183], v[22:25]
	v_mfma_f32_16x16x32_bf16 v[34:37], v[198:201], v[190:193], v[34:37]
	v_mfma_f32_16x16x32_bf16 v[18:21], v[206:209], v[190:193], v[18:21]
	s_add_i32 s45, s45, 2
	s_add_u32 s28, s28, 0x100
	s_addc_u32 s29, s29, 0
	s_cmp_gt_u32 s45, 13
	s_mov_b64 s[6:7], s[88:89]
	s_barrier
	s_cbranch_scc0 .LBB0_919
	s_waitcnt lgkmcnt(0)
	v_mov_b32_e32 v131, v252
	s_lshl_b32 s88, s5, 7
	v_bfe_u32 v130, v131, 4, 2
	v_and_b32_e32 v134, 15, v131
	v_lshlrev_b32_e32 v0, 4, v130
	s_ashr_i32 s89, s88, 31
	s_lshl_b32 s15, s4, 8
	v_or3_b32 v135, v0, s97, v134
	s_lshl_b64 s[4:5], s[88:89], 2
	v_lshrrev_b32_e32 v140, 1, v135
	s_add_u32 s4, s73, s4
	s_addc_u32 s5, s74, s5
	v_lshlrev_b32_e32 v0, 2, v140
	v_and_b32_e32 v144, 1, v131
	v_lshl_add_u64 v[132:133], s[4:5], 0, v[0:1]
	v_cmp_eq_u32_e32 vcc, 1, v144
	v_mov_b32_e32 v0, 0xb00
	s_movk_i32 s4, 0x5000
	v_cndmask_b32_e32 v141, 0, v0, vcc
	v_lshlrev_b32_e32 v0, 2, v141
	v_lshl_add_u64 v[132:133], v[132:133], 0, v[0:1]
	v_add_co_u32_e32 v138, vcc, s4, v132
	s_mov_b32 s4, 0xb000
	s_nop 0
	v_addc_co_u32_e32 v139, vcc, 0, v133, vcc
	global_load_dword v136, v[132:133], off
	global_load_dword v137, v[138:139], off offset:2048
	v_add_co_u32_e32 v132, vcc, s4, v132
	v_add_u32_e32 v0, s88, v141
	s_nop 0
	v_addc_co_u32_e32 v133, vcc, 0, v133, vcc
	global_load_dword v138, v[132:133], off
	v_or_b32_e32 v132, v140, v0
	v_ashrrev_i32_e32 v133, 31, v132
	v_lshl_add_u64 v[132:133], v[132:133], 2, s[12:13]
	global_load_dword v139, v[132:133], off
	v_lshl_add_u32 v0, v135, 4, s78
	v_and_b32_e32 v135, 63, v131
	v_cmp_eq_u32_e32 vcc, 0, v144
	s_waitcnt vmcnt(0)
	ds_write_b128 v0, v[136:139]
	v_or_b32_e32 v0, s97, v135
	v_lshrrev_b32_e32 v0, 1, v0
	v_and_or_b32 v131, v0, 63, s55
	v_add_u32_e32 v132, s15, v131
	v_ashrrev_i32_e32 v133, 31, v132
	v_lshlrev_b64 v[132:133], 6, v[132:133]
	v_lshl_add_u64 v[132:133], s[10:11], 0, v[132:133]
	v_lshlrev_b32_e32 v0, 5, v144
	v_lshl_add_u64 v[132:133], v[132:133], 0, v[0:1]
	global_load_dwordx4 v[136:139], v[132:133], off offset:16
	global_load_dwordx4 v[140:143], v[132:133], off
	s_waitcnt vmcnt(0)
	v_add_f32_e32 v133, v138, v139
	v_add_f32_e32 v0, v140, v141
	v_add_f32_e32 v132, v142, v143
	v_add_f32_e32 v0, v0, v132
	v_add_f32_e32 v132, v136, v137
	v_add_f32_e32 v132, v132, v133
	v_add_f32_e32 v0, v0, v132
	v_lshlrev_b32_e32 v132, 2, v135
	v_xor_b32_e32 v132, 4, v132
	ds_bpermute_b32 v132, v132, v0
	s_and_saveexec_b64 s[4:5], vcc
	s_cbranch_execz .LBB0_922
	s_waitcnt lgkmcnt(0)
	v_add_f32_e32 v0, v0, v132
	v_mov_b32_e32 v132, 0x358637bd
	v_fmamk_f32 v0, v0, 0x3a800000, v132
	s_mov_b32 s6, 0x800000
	v_mul_f32_e32 v132, 0x4b800000, v0
	v_cmp_gt_f32_e32 vcc, s6, v0
	v_lshl_add_u32 v131, v131, 2, 0
	v_add_u32_e32 v131, 0x20000, v131
	v_cndmask_b32_e32 v0, v0, v132, vcc
	v_rsq_f32_e32 v0, v0
	s_nop 0
	v_mul_f32_e32 v132, 0x45800000, v0
	v_cndmask_b32_e32 v0, v0, v132, vcc
	ds_write_b32 v131, v0

.LBB0_1089:
	s_add_u32 s34, s84, 0x100
	v_mov_b32_e32 v2, 0
	s_addc_u32 s78, s85, 0
	s_mov_b32 s79, -2
	s_waitcnt lgkmcnt(0)
	v_mov_b32_e32 v3, v2
	v_mov_b32_e32 v4, v2
	v_mov_b32_e32 v5, v2
	v_mov_b32_e32 v6, v2
	v_mov_b32_e32 v7, v2
	v_mov_b32_e32 v8, v2
	v_mov_b32_e32 v9, v2
	v_mov_b32_e32 v18, v2
	v_mov_b32_e32 v19, v2
	v_mov_b32_e32 v20, v2
	v_mov_b32_e32 v21, v2
	v_mov_b32_e32 v22, v2
	v_mov_b32_e32 v23, v2
	v_mov_b32_e32 v24, v2
	v_mov_b32_e32 v25, v2
	v_mov_b32_e32 v34, v2
	v_mov_b32_e32 v35, v2
	v_mov_b32_e32 v36, v2
	v_mov_b32_e32 v37, v2
	v_mov_b32_e32 v38, v2
	v_mov_b32_e32 v39, v2
	v_mov_b32_e32 v40, v2
	v_mov_b32_e32 v41, v2
	v_mov_b32_e32 v50, v2
	v_mov_b32_e32 v51, v2
	v_mov_b32_e32 v52, v2
	v_mov_b32_e32 v53, v2
	v_mov_b32_e32 v54, v2
	v_mov_b32_e32 v55, v2
	v_mov_b32_e32 v56, v2
	v_mov_b32_e32 v57, v2
	v_mov_b32_e32 v10, v2
	v_mov_b32_e32 v11, v2
	v_mov_b32_e32 v12, v2
	v_mov_b32_e32 v13, v2
	v_mov_b32_e32 v14, v2
	v_mov_b32_e32 v15, v2
	v_mov_b32_e32 v16, v2
	v_mov_b32_e32 v17, v2
	v_mov_b32_e32 v26, v2
	v_mov_b32_e32 v27, v2
	v_mov_b32_e32 v28, v2
	v_mov_b32_e32 v29, v2
	v_mov_b32_e32 v30, v2
	v_mov_b32_e32 v31, v2
	v_mov_b32_e32 v32, v2
	v_mov_b32_e32 v33, v2
	v_mov_b32_e32 v42, v2
	v_mov_b32_e32 v43, v2
	v_mov_b32_e32 v44, v2
	v_mov_b32_e32 v45, v2
	v_mov_b32_e32 v46, v2
	v_mov_b32_e32 v47, v2
	v_mov_b32_e32 v48, v2
	v_mov_b32_e32 v49, v2
	v_mov_b32_e32 v58, v2
	v_mov_b32_e32 v59, v2
	v_mov_b32_e32 v60, v2
	v_mov_b32_e32 v61, v2
	v_mov_b32_e32 v62, v2
	v_mov_b32_e32 v63, v2
	v_mov_b32_e32 v64, v2
	v_mov_b32_e32 v65, v2
	v_mov_b32_e32 v66, v2
	v_mov_b32_e32 v67, v2
	v_mov_b32_e32 v68, v2
	v_mov_b32_e32 v69, v2
	v_mov_b32_e32 v70, v2
	v_mov_b32_e32 v71, v2
	v_mov_b32_e32 v72, v2
	v_mov_b32_e32 v73, v2
	v_mov_b32_e32 v82, v2
	v_mov_b32_e32 v83, v2
	v_mov_b32_e32 v84, v2
	v_mov_b32_e32 v85, v2
	v_mov_b32_e32 v86, v2
	v_mov_b32_e32 v87, v2
	v_mov_b32_e32 v88, v2
	v_mov_b32_e32 v89, v2
	v_mov_b32_e32 v98, v2
	v_mov_b32_e32 v99, v2
	v_mov_b32_e32 v100, v2
	v_mov_b32_e32 v101, v2
	v_mov_b32_e32 v102, v2
	v_mov_b32_e32 v103, v2
	v_mov_b32_e32 v104, v2
	v_mov_b32_e32 v105, v2
	v_mov_b32_e32 v114, v2
	v_mov_b32_e32 v115, v2
	v_mov_b32_e32 v116, v2
	v_mov_b32_e32 v117, v2
	v_mov_b32_e32 v118, v2
	v_mov_b32_e32 v119, v2
	v_mov_b32_e32 v120, v2
	v_mov_b32_e32 v121, v2
	v_mov_b32_e32 v74, v2
	v_mov_b32_e32 v75, v2
	v_mov_b32_e32 v76, v2
	v_mov_b32_e32 v77, v2
	v_mov_b32_e32 v78, v2
	v_mov_b32_e32 v79, v2
	v_mov_b32_e32 v80, v2
	v_mov_b32_e32 v81, v2
	v_mov_b32_e32 v90, v2
	v_mov_b32_e32 v91, v2
	v_mov_b32_e32 v92, v2
	v_mov_b32_e32 v93, v2
	v_mov_b32_e32 v94, v2
	v_mov_b32_e32 v95, v2
	v_mov_b32_e32 v96, v2
	v_mov_b32_e32 v97, v2
	v_mov_b32_e32 v106, v2
	v_mov_b32_e32 v107, v2
	v_mov_b32_e32 v108, v2
	v_mov_b32_e32 v109, v2
	v_mov_b32_e32 v110, v2
	v_mov_b32_e32 v111, v2
	v_mov_b32_e32 v112, v2
	v_mov_b32_e32 v113, v2
	v_mov_b32_e32 v122, v2
	v_mov_b32_e32 v123, v2
	v_mov_b32_e32 v124, v2
	v_mov_b32_e32 v125, v2
	v_mov_b32_e32 v126, v2
	v_mov_b32_e32 v127, v2
	v_mov_b32_e32 v128, v2
	v_mov_b32_e32 v129, v2
	s_add_i32 s90, 0, 0x10000
	v_add_u32_e32 v142, s90, v212
	ds_read_b128 v[130:133], v142
	ds_read_b128 v[134:137], v142 offset:1024
	ds_read_b128 v[138:141], v142 offset:2048
	ds_read_b128 v[142:145], v142 offset:3072
.LBB0_1090:
	s_add_u32 s84, s16, 0x100
	s_addc_u32 s85, s17, 0
	s_cmp_eq_u32 s79, 40
	s_cselect_b32 s89, s5, s85
	s_cselect_b32 s88, s4, s84
	s_cselect_b32 s87, s7, s78
	s_cselect_b32 s86, s6, s34
	v_lshl_add_u64 v[178:179], s[16:17], 0, v[196:197]
	s_add_i32 m0, s39, 0xc000
	ds_read_b128 v[146:149], v213
	ds_read_b128 v[150:153], v213 offset:1024
	ds_read_b128 v[154:157], v213 offset:2048
	ds_read_b128 v[158:161], v213 offset:3072
	ds_read_b128 v[162:165], v213 offset:4096
	ds_read_b128 v[166:169], v213 offset:5120
	ds_read_b128 v[170:173], v213 offset:6144
	ds_read_b128 v[174:177], v213 offset:7168
	global_load_lds_dwordx4 v[178:179], off
	s_add_i32 m0, s39, 0xe000
	v_lshl_add_u64 v[178:179], s[16:17], 0, v[198:199]
	global_load_lds_dwordx4 v[178:179], off
	s_waitcnt lgkmcnt(8)
	s_barrier
	s_waitcnt lgkmcnt(0)
	v_mfma_f32_16x16x32_bf16 v[126:129], v[130:133], v[146:149], v[126:129]
	v_mfma_f32_16x16x32_bf16 v[122:125], v[138:141], v[146:149], v[122:125]
	v_mfma_f32_16x16x32_bf16 v[110:113], v[130:133], v[154:157], v[110:113]
	v_mfma_f32_16x16x32_bf16 v[106:109], v[138:141], v[154:157], v[106:109]
	v_mfma_f32_16x16x32_bf16 v[94:97], v[130:133], v[162:165], v[94:97]
	v_mfma_f32_16x16x32_bf16 v[90:93], v[138:141], v[162:165], v[90:93]
	v_mfma_f32_16x16x32_bf16 v[78:81], v[130:133], v[170:173], v[78:81]
	v_mfma_f32_16x16x32_bf16 v[74:77], v[138:141], v[170:173], v[74:77]
	v_mfma_f32_16x16x32_bf16 v[126:129], v[134:137], v[150:153], v[126:129]
	v_mfma_f32_16x16x32_bf16 v[122:125], v[142:145], v[150:153], v[122:125]
	v_mfma_f32_16x16x32_bf16 v[110:113], v[134:137], v[158:161], v[110:113]
	v_mfma_f32_16x16x32_bf16 v[106:109], v[142:145], v[158:161], v[106:109]
	v_mfma_f32_16x16x32_bf16 v[94:97], v[134:137], v[166:169], v[94:97]
	v_mfma_f32_16x16x32_bf16 v[90:93], v[142:145], v[166:169], v[90:93]
	v_mfma_f32_16x16x32_bf16 v[78:81], v[134:137], v[174:177], v[78:81]
	v_mfma_f32_16x16x32_bf16 v[74:77], v[142:145], v[174:177], v[74:77]
	s_barrier
	s_add_i32 s91, 0, 0x14000
	v_add_u32_e32 v186, s91, v212
	s_add_i32 s16, s90, s38
	ds_read_b128 v[178:181], v186
	ds_read_b128 v[182:185], v186 offset:1024
	ds_read_b128 v[200:203], v186 offset:2048
	ds_read_b128 v[204:207], v186 offset:3072
	v_lshl_add_u64 v[186:187], s[86:87], 0, v[0:1]
	s_mov_b32 m0, s16
	v_lshl_add_u64 v[208:209], s[86:87], 0, v[194:195]
	global_load_lds_dwordx4 v[186:187], off
	s_add_i32 m0, s16, 0x2000
	s_nop 0
	global_load_lds_dwordx4 v[208:209], off
	s_barrier
	s_waitcnt lgkmcnt(0)
	v_mfma_f32_16x16x32_bf16 v[118:121], v[178:181], v[146:149], v[118:121]
	v_mfma_f32_16x16x32_bf16 v[114:117], v[200:203], v[146:149], v[114:117]
	v_mfma_f32_16x16x32_bf16 v[102:105], v[178:181], v[154:157], v[102:105]
	v_mfma_f32_16x16x32_bf16 v[98:101], v[200:203], v[154:157], v[98:101]
	v_mfma_f32_16x16x32_bf16 v[86:89], v[178:181], v[162:165], v[86:89]
	v_mfma_f32_16x16x32_bf16 v[82:85], v[200:203], v[162:165], v[82:85]
	v_mfma_f32_16x16x32_bf16 v[70:73], v[178:181], v[170:173], v[70:73]
	v_mfma_f32_16x16x32_bf16 v[66:69], v[200:203], v[170:173], v[66:69]
	v_mfma_f32_16x16x32_bf16 v[118:121], v[182:185], v[150:153], v[118:121]
	v_mfma_f32_16x16x32_bf16 v[114:117], v[204:207], v[150:153], v[114:117]
	v_mfma_f32_16x16x32_bf16 v[102:105], v[182:185], v[158:161], v[102:105]
	v_mfma_f32_16x16x32_bf16 v[98:101], v[204:207], v[158:161], v[98:101]
	v_mfma_f32_16x16x32_bf16 v[86:89], v[182:185], v[166:169], v[86:89]
	v_mfma_f32_16x16x32_bf16 v[82:85], v[204:207], v[166:169], v[82:85]
	v_mfma_f32_16x16x32_bf16 v[70:73], v[182:185], v[174:177], v[70:73]
	v_mfma_f32_16x16x32_bf16 v[66:69], v[204:207], v[174:177], v[66:69]
	s_mov_b32 m0, s39
	v_lshl_add_u64 v[210:211], s[88:89], 0, v[190:191]
	s_barrier
	ds_read_b128 v[146:149], v213 offset:16384
	ds_read_b128 v[150:153], v213 offset:17408
	ds_read_b128 v[154:157], v213 offset:18432
	ds_read_b128 v[158:161], v213 offset:19456
	ds_read_b128 v[162:165], v213 offset:20480
	ds_read_b128 v[166:169], v213 offset:21504
	ds_read_b128 v[170:173], v213 offset:22528
	ds_read_b128 v[174:177], v213 offset:23552
	global_load_lds_dwordx4 v[210:211], off
	s_mov_b32 m0, s42
	v_lshl_add_u64 v[214:215], s[88:89], 0, v[192:193]
	global_load_lds_dwordx4 v[214:215], off
	s_waitcnt vmcnt(10)
	s_barrier
	s_waitcnt lgkmcnt(0)
	v_mfma_f32_16x16x32_bf16 v[62:65], v[130:133], v[146:149], v[62:65]
	v_mfma_f32_16x16x32_bf16 v[58:61], v[138:141], v[146:149], v[58:61]
	v_mfma_f32_16x16x32_bf16 v[46:49], v[130:133], v[154:157], v[46:49]
	v_mfma_f32_16x16x32_bf16 v[42:45], v[138:141], v[154:157], v[42:45]
	v_mfma_f32_16x16x32_bf16 v[30:33], v[130:133], v[162:165], v[30:33]
	v_mfma_f32_16x16x32_bf16 v[26:29], v[138:141], v[162:165], v[26:29]
	v_mfma_f32_16x16x32_bf16 v[14:17], v[130:133], v[170:173], v[14:17]
	v_mfma_f32_16x16x32_bf16 v[10:13], v[138:141], v[170:173], v[10:13]
	v_mfma_f32_16x16x32_bf16 v[62:65], v[134:137], v[150:153], v[62:65]
	v_mfma_f32_16x16x32_bf16 v[58:61], v[142:145], v[150:153], v[58:61]
	v_mfma_f32_16x16x32_bf16 v[46:49], v[134:137], v[158:161], v[46:49]
	v_mfma_f32_16x16x32_bf16 v[42:45], v[142:145], v[158:161], v[42:45]
	v_mfma_f32_16x16x32_bf16 v[30:33], v[134:137], v[166:169], v[30:33]
	v_mfma_f32_16x16x32_bf16 v[26:29], v[142:145], v[166:169], v[26:29]
	v_mfma_f32_16x16x32_bf16 v[14:17], v[134:137], v[174:177], v[14:17]
	v_mfma_f32_16x16x32_bf16 v[10:13], v[142:145], v[174:177], v[10:13]
	s_barrier
	s_add_u32 s16, s86, 0xb0000
	s_addc_u32 s17, s87, 0
	s_add_i32 s90, s91, s38
	s_mov_b32 m0, s90
	v_lshl_add_u64 v[130:131], s[16:17], 0, v[0:1]
	global_load_lds_dwordx4 v[130:131], off
	s_add_i32 m0, s90, 0x2000
	v_lshl_add_u64 v[130:131], s[16:17], 0, v[194:195]
	global_load_lds_dwordx4 v[130:131], off
	s_add_i32 s90, 0, 0x18000
	v_add_u32_e32 v142, s90, v212
	ds_read_b128 v[130:133], v142
	ds_read_b128 v[134:137], v142 offset:1024
	ds_read_b128 v[138:141], v142 offset:2048
	ds_read_b128 v[142:145], v142 offset:3072
	s_waitcnt vmcnt(6)
	s_barrier
	v_mfma_f32_16x16x32_bf16 v[54:57], v[178:181], v[146:149], v[54:57]
	v_mfma_f32_16x16x32_bf16 v[50:53], v[200:203], v[146:149], v[50:53]
	v_mfma_f32_16x16x32_bf16 v[38:41], v[178:181], v[154:157], v[38:41]
	v_mfma_f32_16x16x32_bf16 v[34:37], v[200:203], v[154:157], v[34:37]
	v_mfma_f32_16x16x32_bf16 v[22:25], v[178:181], v[162:165], v[22:25]
	v_mfma_f32_16x16x32_bf16 v[18:21], v[200:203], v[162:165], v[18:21]
	v_mfma_f32_16x16x32_bf16 v[6:9], v[178:181], v[170:173], v[6:9]
	v_mfma_f32_16x16x32_bf16 v[2:5], v[200:203], v[170:173], v[2:5]
	v_mfma_f32_16x16x32_bf16 v[54:57], v[182:185], v[150:153], v[54:57]
	v_mfma_f32_16x16x32_bf16 v[50:53], v[204:207], v[150:153], v[50:53]
	v_mfma_f32_16x16x32_bf16 v[38:41], v[182:185], v[158:161], v[38:41]
	v_mfma_f32_16x16x32_bf16 v[34:37], v[204:207], v[158:161], v[34:37]
	v_mfma_f32_16x16x32_bf16 v[22:25], v[182:185], v[166:169], v[22:25]
	v_mfma_f32_16x16x32_bf16 v[18:21], v[204:207], v[166:169], v[18:21]
	v_mfma_f32_16x16x32_bf16 v[6:9], v[182:185], v[174:177], v[6:9]
	v_mfma_f32_16x16x32_bf16 v[2:5], v[204:207], v[174:177], v[2:5]
	s_barrier
	s_add_u32 s16, s88, 0xb0000
	s_addc_u32 s17, s89, 0
	s_mov_b32 m0, s43
	v_lshl_add_u64 v[178:179], s[16:17], 0, v[190:191]
	ds_read_b128 v[146:149], v213 offset:32768
	ds_read_b128 v[150:153], v213 offset:33792
	ds_read_b128 v[154:157], v213 offset:34816
	ds_read_b128 v[158:161], v213 offset:35840
	ds_read_b128 v[162:165], v213 offset:36864
	ds_read_b128 v[166:169], v213 offset:37888
	ds_read_b128 v[170:173], v213 offset:38912
	ds_read_b128 v[174:177], v213 offset:39936
	global_load_lds_dwordx4 v[178:179], off
	s_mov_b32 m0, s44
	v_lshl_add_u64 v[178:179], s[16:17], 0, v[192:193]
	global_load_lds_dwordx4 v[178:179], off
	s_waitcnt lgkmcnt(8)
	s_barrier
	s_waitcnt lgkmcnt(0)
	v_mfma_f32_16x16x32_bf16 v[126:129], v[130:133], v[146:149], v[126:129]
	v_mfma_f32_16x16x32_bf16 v[122:125], v[138:141], v[146:149], v[122:125]
	v_mfma_f32_16x16x32_bf16 v[110:113], v[130:133], v[154:157], v[110:113]
	v_mfma_f32_16x16x32_bf16 v[106:109], v[138:141], v[154:157], v[106:109]
	v_mfma_f32_16x16x32_bf16 v[94:97], v[130:133], v[162:165], v[94:97]
	v_mfma_f32_16x16x32_bf16 v[90:93], v[138:141], v[162:165], v[90:93]
	v_mfma_f32_16x16x32_bf16 v[78:81], v[130:133], v[170:173], v[78:81]
	v_mfma_f32_16x16x32_bf16 v[74:77], v[138:141], v[170:173], v[74:77]
	v_mfma_f32_16x16x32_bf16 v[126:129], v[134:137], v[150:153], v[126:129]
	v_mfma_f32_16x16x32_bf16 v[122:125], v[142:145], v[150:153], v[122:125]
	v_mfma_f32_16x16x32_bf16 v[110:113], v[134:137], v[158:161], v[110:113]
	v_mfma_f32_16x16x32_bf16 v[106:109], v[142:145], v[158:161], v[106:109]
	v_mfma_f32_16x16x32_bf16 v[94:97], v[134:137], v[166:169], v[94:97]
	v_mfma_f32_16x16x32_bf16 v[90:93], v[142:145], v[166:169], v[90:93]
	v_mfma_f32_16x16x32_bf16 v[78:81], v[134:137], v[174:177], v[78:81]
	v_mfma_f32_16x16x32_bf16 v[74:77], v[142:145], v[174:177], v[74:77]
	s_barrier
	s_add_i32 s88, 0, 0x1c000
	s_add_i32 s16, s90, s38
	v_add_u32_e32 v204, s88, v212
	v_lshl_add_u64 v[186:187], v[186:187], 0, s[40:41]
	s_mov_b32 m0, s16
	ds_read_b128 v[178:181], v204
	ds_read_b128 v[182:185], v204 offset:1024
	ds_read_b128 v[200:203], v204 offset:2048
	ds_read_b128 v[204:207], v204 offset:3072
	global_load_lds_dwordx4 v[186:187], off
	s_add_i32 m0, s16, 0x2000
	v_lshl_add_u64 v[186:187], v[208:209], 0, s[40:41]
	global_load_lds_dwordx4 v[186:187], off
	s_barrier
	s_waitcnt lgkmcnt(0)
	v_mfma_f32_16x16x32_bf16 v[118:121], v[178:181], v[146:149], v[118:121]
	v_mfma_f32_16x16x32_bf16 v[114:117], v[200:203], v[146:149], v[114:117]
	v_mfma_f32_16x16x32_bf16 v[102:105], v[178:181], v[154:157], v[102:105]
	v_mfma_f32_16x16x32_bf16 v[98:101], v[200:203], v[154:157], v[98:101]
	v_mfma_f32_16x16x32_bf16 v[86:89], v[178:181], v[162:165], v[86:89]
	v_mfma_f32_16x16x32_bf16 v[82:85], v[200:203], v[162:165], v[82:85]
	v_mfma_f32_16x16x32_bf16 v[70:73], v[178:181], v[170:173], v[70:73]
	v_mfma_f32_16x16x32_bf16 v[66:69], v[200:203], v[170:173], v[66:69]
	v_mfma_f32_16x16x32_bf16 v[118:121], v[182:185], v[150:153], v[118:121]
	v_mfma_f32_16x16x32_bf16 v[114:117], v[204:207], v[150:153], v[114:117]
	v_mfma_f32_16x16x32_bf16 v[102:105], v[182:185], v[158:161], v[102:105]
	v_mfma_f32_16x16x32_bf16 v[98:101], v[204:207], v[158:161], v[98:101]
	v_mfma_f32_16x16x32_bf16 v[86:89], v[182:185], v[166:169], v[86:89]
	v_mfma_f32_16x16x32_bf16 v[82:85], v[204:207], v[166:169], v[82:85]
	v_mfma_f32_16x16x32_bf16 v[70:73], v[182:185], v[174:177], v[70:73]
	v_mfma_f32_16x16x32_bf16 v[66:69], v[204:207], v[174:177], v[66:69]
	s_mov_b32 m0, s60
	v_lshl_add_u64 v[186:187], v[210:211], 0, s[40:41]
	s_barrier
	ds_read_b128 v[146:149], v213 offset:49152
	ds_read_b128 v[150:153], v213 offset:50176
	ds_read_b128 v[154:157], v213 offset:51200
	ds_read_b128 v[158:161], v213 offset:52224
	ds_read_b128 v[162:165], v213 offset:53248
	ds_read_b128 v[166:169], v213 offset:54272
	ds_read_b128 v[170:173], v213 offset:55296
	ds_read_b128 v[174:177], v213 offset:56320
	global_load_lds_dwordx4 v[186:187], off
	s_mov_b32 m0, s61
	v_lshl_add_u64 v[186:187], v[214:215], 0, s[40:41]
	global_load_lds_dwordx4 v[186:187], off
	s_waitcnt vmcnt(10)
	s_barrier
	s_waitcnt lgkmcnt(0)
	v_mfma_f32_16x16x32_bf16 v[62:65], v[130:133], v[146:149], v[62:65]
	v_mfma_f32_16x16x32_bf16 v[58:61], v[138:141], v[146:149], v[58:61]
	v_mfma_f32_16x16x32_bf16 v[46:49], v[130:133], v[154:157], v[46:49]
	v_mfma_f32_16x16x32_bf16 v[42:45], v[138:141], v[154:157], v[42:45]
	v_mfma_f32_16x16x32_bf16 v[30:33], v[130:133], v[162:165], v[30:33]
	v_mfma_f32_16x16x32_bf16 v[26:29], v[138:141], v[162:165], v[26:29]
	v_mfma_f32_16x16x32_bf16 v[14:17], v[130:133], v[170:173], v[14:17]
	v_mfma_f32_16x16x32_bf16 v[10:13], v[138:141], v[170:173], v[10:13]
	v_mfma_f32_16x16x32_bf16 v[62:65], v[134:137], v[150:153], v[62:65]
	v_mfma_f32_16x16x32_bf16 v[58:61], v[142:145], v[150:153], v[58:61]
	v_mfma_f32_16x16x32_bf16 v[46:49], v[134:137], v[158:161], v[46:49]
	v_mfma_f32_16x16x32_bf16 v[42:45], v[142:145], v[158:161], v[42:45]
	v_mfma_f32_16x16x32_bf16 v[30:33], v[134:137], v[166:169], v[30:33]
	v_mfma_f32_16x16x32_bf16 v[26:29], v[142:145], v[166:169], v[26:29]
	v_mfma_f32_16x16x32_bf16 v[14:17], v[134:137], v[174:177], v[14:17]
	v_mfma_f32_16x16x32_bf16 v[10:13], v[142:145], v[174:177], v[10:13]
	s_barrier
	s_add_u32 s16, s86, 0xb0080
	s_addc_u32 s17, s87, 0
	s_add_i32 s86, s88, s38
	s_mov_b32 m0, s86
	v_lshl_add_u64 v[130:131], s[16:17], 0, v[0:1]
	global_load_lds_dwordx4 v[130:131], off
	s_add_i32 m0, s86, 0x2000
	v_lshl_add_u64 v[130:131], s[16:17], 0, v[194:195]
	global_load_lds_dwordx4 v[130:131], off
	s_add_i32 s90, 0, 0x10000
	v_add_u32_e32 v142, s90, v212
	ds_read_b128 v[130:133], v142
	ds_read_b128 v[134:137], v142 offset:1024
	ds_read_b128 v[138:141], v142 offset:2048
	ds_read_b128 v[142:145], v142 offset:3072
	s_waitcnt vmcnt(6)
	s_barrier
	v_mfma_f32_16x16x32_bf16 v[54:57], v[178:181], v[146:149], v[54:57]
	v_mfma_f32_16x16x32_bf16 v[50:53], v[200:203], v[146:149], v[50:53]
	v_mfma_f32_16x16x32_bf16 v[38:41], v[178:181], v[154:157], v[38:41]
	v_mfma_f32_16x16x32_bf16 v[34:37], v[200:203], v[154:157], v[34:37]
	v_mfma_f32_16x16x32_bf16 v[22:25], v[178:181], v[162:165], v[22:25]
	v_mfma_f32_16x16x32_bf16 v[18:21], v[200:203], v[162:165], v[18:21]
	v_mfma_f32_16x16x32_bf16 v[6:9], v[178:181], v[170:173], v[6:9]
	v_mfma_f32_16x16x32_bf16 v[2:5], v[200:203], v[170:173], v[2:5]
	v_mfma_f32_16x16x32_bf16 v[54:57], v[182:185], v[150:153], v[54:57]
	v_mfma_f32_16x16x32_bf16 v[50:53], v[204:207], v[150:153], v[50:53]
	v_mfma_f32_16x16x32_bf16 v[38:41], v[182:185], v[158:161], v[38:41]
	v_mfma_f32_16x16x32_bf16 v[34:37], v[204:207], v[158:161], v[34:37]
	v_mfma_f32_16x16x32_bf16 v[22:25], v[182:185], v[166:169], v[22:25]
	v_mfma_f32_16x16x32_bf16 v[18:21], v[204:207], v[166:169], v[18:21]
	v_mfma_f32_16x16x32_bf16 v[6:9], v[182:185], v[174:177], v[6:9]
	v_mfma_f32_16x16x32_bf16 v[2:5], v[204:207], v[174:177], v[2:5]
	s_add_i32 s79, s79, 2
	s_add_u32 s34, s34, 0x100
	s_addc_u32 s78, s78, 0
	s_cmp_gt_u32 s79, 41
	s_mov_b64 s[16:17], s[84:85]
	s_barrier
	s_cbranch_scc0 .LBB0_1090
	s_waitcnt lgkmcnt(0)
	s_lshl_b32 s16, s23, 8
	v_mov_b32_e32 v186, v252
	s_add_i32 s16, s16, s47
	s_nop 0
	v_and_or_b32 v202, v186, 15, s16
	s_lshl_b32 s16, s22, 8
	s_or_b32 s16, s16, s55
	v_lshrrev_b32_e32 v130, 1, v186
	v_and_or_b32 v200, v130, 24, s16
	v_ashrrev_i32_e32 v201, 31, v200
	v_ashrrev_i32_e32 v203, 31, v202
	v_lshl_add_u64 v[204:205], v[200:201], 2, s[12:13]
	v_lshlrev_b64 v[130:131], 12, v[202:203]
	v_lshl_add_u64 v[130:131], v[204:205], 0, v[130:131]
	global_load_dwordx4 v[216:219], v[130:131], off offset:16
	global_load_dwordx4 v[220:223], v[130:131], off
	global_load_dwordx4 v[178:181], v[130:131], off offset:528
	global_load_dwordx4 v[182:185], v[130:131], off offset:512
	v_or_b32_e32 v210, 16, v202
	v_ashrrev_i32_e32 v211, 31, v210
	v_lshlrev_b64 v[130:131], 12, v[210:211]
	v_or_b32_e32 v208, 32, v202
	v_lshl_add_u64 v[130:131], v[204:205], 0, v[130:131]
	v_ashrrev_i32_e32 v209, 31, v208
	global_load_dwordx4 v[170:173], v[130:131], off offset:16
	global_load_dwordx4 v[174:177], v[130:131], off
	global_load_dwordx4 v[162:165], v[130:131], off offset:528
	global_load_dwordx4 v[166:169], v[130:131], off offset:512
	v_lshlrev_b64 v[130:131], 12, v[208:209]
	v_or_b32_e32 v206, 48, v202
	v_lshl_add_u64 v[130:131], v[204:205], 0, v[130:131]
	v_ashrrev_i32_e32 v207, 31, v206
	global_load_dwordx4 v[154:157], v[130:131], off offset:16
	global_load_dwordx4 v[158:161], v[130:131], off
	global_load_dwordx4 v[138:141], v[130:131], off offset:528
	global_load_dwordx4 v[142:145], v[130:131], off offset:512
	v_lshlrev_b64 v[130:131], 12, v[206:207]
	v_lshl_add_u64 v[134:135], v[204:205], 0, v[130:131]
	global_load_dwordx4 v[146:149], v[134:135], off offset:16
	global_load_dwordx4 v[150:153], v[134:135], off
	global_load_dwordx4 v[130:133], v[134:135], off offset:528
	s_nop 0
	global_load_dwordx4 v[134:137], v[134:135], off offset:512
	v_and_b32_e32 v186, 63, v186
	v_lshlrev_b32_e32 v187, 2, v186
	v_xor_b32_e32 v215, 64, v187
	v_xor_b32_e32 v214, 0x80, v187
	v_cmp_gt_u32_e32 vcc, 16, v186
	v_lshlrev_b64 v[186:187], 10, v[202:203]
	v_lshl_add_u64 v[186:187], v[186:187], 0, v[200:201]
	s_lshl_b32 s16, s22, 2
	s_ashr_i32 s17, s16, 31
	s_waitcnt vmcnt(0)
	v_pk_add_f32 v[124:125], v[124:125], v[218:219]
	v_pk_add_f32 v[128:129], v[128:129], v[222:223]
	v_pk_add_f32 v[126:127], v[126:127], v[220:221]
	v_pk_mul_f32 v[218:219], v[128:129], v[128:129]
	v_pk_mul_f32 v[220:221], v[126:127], v[126:127]
	v_pk_add_f32 v[122:123], v[122:123], v[216:217]
	v_lshl_add_u64 v[216:217], v[186:187], 2, s[14:15]
	v_add_f32_e32 v220, v220, v221
	v_add_f32_e32 v218, v218, v219
	global_store_dwordx4 v[216:217], v[126:129], off
	global_store_dwordx4 v[216:217], v[122:125], off offset:16
	v_add_f32_e32 v222, v220, v218
	v_pk_mul_f32 v[220:221], v[122:123], v[122:123]
	v_cvt_pk_bf16_f32 v126, v126, v127
	v_cvt_pk_bf16_f32 v127, v128, v129
	v_cvt_pk_bf16_f32 v128, v122, v123
	v_cvt_pk_bf16_f32 v129, v124, v125
	v_lshl_add_u64 v[122:123], v[186:187], 1, s[80:81]
	v_pk_add_f32 v[120:121], v[120:121], v[184:185]
	v_pk_add_f32 v[118:119], v[118:119], v[182:183]
	v_pk_mul_f32 v[218:219], v[124:125], v[124:125]
	global_store_dwordx4 v[122:123], v[126:129], off
	v_pk_mul_f32 v[124:125], v[120:121], v[120:121]
	v_pk_add_f32 v[116:117], v[116:117], v[180:181]
	v_pk_mul_f32 v[126:127], v[118:119], v[118:119]
	v_pk_add_f32 v[114:115], v[114:115], v[178:179]
	v_add_f32_e32 v126, v126, v127
	v_add_f32_e32 v124, v124, v125
	v_add_f32_e32 v128, v126, v124
	v_pk_mul_f32 v[124:125], v[116:117], v[116:117]
	v_pk_mul_f32 v[126:127], v[114:115], v[114:115]
	v_add_f32_e32 v220, v220, v221
	v_add_f32_e32 v218, v218, v219
	v_add_f32_e32 v126, v126, v127
	v_add_f32_e32 v124, v124, v125
	v_add_f32_e32 v218, v220, v218
	v_add_f32_e32 v124, v126, v124
	v_add_f32_e32 v218, v222, v218
	v_add_f32_e32 v124, v128, v124
	v_add_f32_e32 v124, v218, v124
	global_store_dwordx4 v[216:217], v[118:121], off offset:512
	global_store_dwordx4 v[216:217], v[114:117], off offset:528
	s_nop 0
	v_cvt_pk_bf16_f32 v118, v118, v119
	v_cvt_pk_bf16_f32 v119, v120, v121
	v_cvt_pk_bf16_f32 v120, v114, v115
	ds_bpermute_b32 v114, v215, v124
	v_cvt_pk_bf16_f32 v121, v116, v117
	global_store_dwordx4 v[122:123], v[118:121], off offset:256
	s_waitcnt lgkmcnt(0)
	v_add_f32_e32 v114, v124, v114
	ds_bpermute_b32 v115, v214, v114
	s_and_saveexec_b64 s[22:23], vcc
	s_cbranch_execz .LBB0_1093
	v_lshlrev_b64 v[116:117], 6, v[202:203]
	v_lshl_add_u64 v[116:117], s[82:83], 0, v[116:117]
	v_lshl_add_u64 v[116:117], s[16:17], 2, v[116:117]
	s_lshl_b32 s34, s45, 2
	v_lshl_add_u64 v[116:117], v[116:117], 0, s[34:35]
	s_waitcnt lgkmcnt(0)
	v_add_f32_e32 v114, v114, v115
	global_store_dword v[116:117], v114, off

.LBB0_1208:
	s_ashr_i32 s13, s12, 31
	v_cmp_lt_i64_e32 vcc, s[14:15], v[230:231]
	s_lshl_b64 s[14:15], s[12:13], 19
	s_add_u32 s14, s80, s14
	s_addc_u32 s15, s81, s15
	s_and_b64 s[16:17], vcc, exec
	s_cselect_b32 s13, s15, s89
	s_cselect_b32 s22, s14, s88
	s_ashr_i32 s7, s6, 31
	s_lshl_b64 s[16:17], s[6:7], 19
	s_add_u32 s16, s36, s16
	s_addc_u32 s17, s37, s17
	s_and_b64 s[92:93], vcc, exec
	s_cselect_b32 s7, s17, s91
	s_cselect_b32 s23, s16, s90
	s_add_u32 s88, s88, 0x40080
	s_addc_u32 s89, s89, 0
	s_add_u32 s34, s90, 0x100
	v_mov_b32_e32 v2, 0
	s_addc_u32 s79, s91, 0
	s_mov_b32 s85, -2
	v_mov_b32_e32 v3, v2
	v_mov_b32_e32 v4, v2
	v_mov_b32_e32 v5, v2
	v_mov_b32_e32 v6, v2
	v_mov_b32_e32 v7, v2
	v_mov_b32_e32 v8, v2
	v_mov_b32_e32 v9, v2
	v_mov_b32_e32 v18, v2
	v_mov_b32_e32 v19, v2
	v_mov_b32_e32 v20, v2
	v_mov_b32_e32 v21, v2
	v_mov_b32_e32 v22, v2
	v_mov_b32_e32 v23, v2
	v_mov_b32_e32 v24, v2
	v_mov_b32_e32 v25, v2
	v_mov_b32_e32 v34, v2
	v_mov_b32_e32 v35, v2
	v_mov_b32_e32 v36, v2
	v_mov_b32_e32 v37, v2
	v_mov_b32_e32 v38, v2
	v_mov_b32_e32 v39, v2
	v_mov_b32_e32 v40, v2
	v_mov_b32_e32 v41, v2
	v_mov_b32_e32 v50, v2
	v_mov_b32_e32 v51, v2
	v_mov_b32_e32 v52, v2
	v_mov_b32_e32 v53, v2
	v_mov_b32_e32 v54, v2
	v_mov_b32_e32 v55, v2
	v_mov_b32_e32 v56, v2
	v_mov_b32_e32 v57, v2
	v_mov_b32_e32 v10, v2
	v_mov_b32_e32 v11, v2
	v_mov_b32_e32 v12, v2
	v_mov_b32_e32 v13, v2
	v_mov_b32_e32 v14, v2
	v_mov_b32_e32 v15, v2
	v_mov_b32_e32 v16, v2
	v_mov_b32_e32 v17, v2
	v_mov_b32_e32 v26, v2
	v_mov_b32_e32 v27, v2
	v_mov_b32_e32 v28, v2
	v_mov_b32_e32 v29, v2
	v_mov_b32_e32 v30, v2
	v_mov_b32_e32 v31, v2
	v_mov_b32_e32 v32, v2
	v_mov_b32_e32 v33, v2
	v_mov_b32_e32 v42, v2
	v_mov_b32_e32 v43, v2
	v_mov_b32_e32 v44, v2
	v_mov_b32_e32 v45, v2
	v_mov_b32_e32 v46, v2
	v_mov_b32_e32 v47, v2
	v_mov_b32_e32 v48, v2
	v_mov_b32_e32 v49, v2
	v_mov_b32_e32 v58, v2
	v_mov_b32_e32 v59, v2
	v_mov_b32_e32 v60, v2
	v_mov_b32_e32 v61, v2
	v_mov_b32_e32 v62, v2
	v_mov_b32_e32 v63, v2
	v_mov_b32_e32 v64, v2
	v_mov_b32_e32 v65, v2
	v_mov_b32_e32 v66, v2
	v_mov_b32_e32 v67, v2
	v_mov_b32_e32 v68, v2
	v_mov_b32_e32 v69, v2
	v_mov_b32_e32 v70, v2
	v_mov_b32_e32 v71, v2
	v_mov_b32_e32 v72, v2
	v_mov_b32_e32 v73, v2
	v_mov_b32_e32 v82, v2
	v_mov_b32_e32 v83, v2
	v_mov_b32_e32 v84, v2
	v_mov_b32_e32 v85, v2
	v_mov_b32_e32 v86, v2
	v_mov_b32_e32 v87, v2
	v_mov_b32_e32 v88, v2
	v_mov_b32_e32 v89, v2
	v_mov_b32_e32 v98, v2
	v_mov_b32_e32 v99, v2
	v_mov_b32_e32 v100, v2
	v_mov_b32_e32 v101, v2
	v_mov_b32_e32 v102, v2
	v_mov_b32_e32 v103, v2
	v_mov_b32_e32 v104, v2
	v_mov_b32_e32 v105, v2
	v_mov_b32_e32 v114, v2
	v_mov_b32_e32 v115, v2
	v_mov_b32_e32 v116, v2
	v_mov_b32_e32 v117, v2
	v_mov_b32_e32 v118, v2
	v_mov_b32_e32 v119, v2
	v_mov_b32_e32 v120, v2
	v_mov_b32_e32 v121, v2
	v_mov_b32_e32 v74, v2
	v_mov_b32_e32 v75, v2
	v_mov_b32_e32 v76, v2
	v_mov_b32_e32 v77, v2
	v_mov_b32_e32 v78, v2
	v_mov_b32_e32 v79, v2
	v_mov_b32_e32 v80, v2
	v_mov_b32_e32 v81, v2
	v_mov_b32_e32 v90, v2
	v_mov_b32_e32 v91, v2
	v_mov_b32_e32 v92, v2
	v_mov_b32_e32 v93, v2
	v_mov_b32_e32 v94, v2
	v_mov_b32_e32 v95, v2
	v_mov_b32_e32 v96, v2
	v_mov_b32_e32 v97, v2
	v_mov_b32_e32 v106, v2
	v_mov_b32_e32 v107, v2
	v_mov_b32_e32 v108, v2
	v_mov_b32_e32 v109, v2
	v_mov_b32_e32 v110, v2
	v_mov_b32_e32 v111, v2
	v_mov_b32_e32 v112, v2
	v_mov_b32_e32 v113, v2
	v_mov_b32_e32 v122, v2
	v_mov_b32_e32 v123, v2
	v_mov_b32_e32 v124, v2
	v_mov_b32_e32 v125, v2
	v_mov_b32_e32 v126, v2
	v_mov_b32_e32 v127, v2
	v_mov_b32_e32 v128, v2
	v_mov_b32_e32 v129, v2
	s_waitcnt lgkmcnt(0)
	s_add_i32 s94, 0, 0x10000
	v_add_u32_e32 v0, s94, v170
	ds_read_b128 v[130:133], v0
	ds_read_b128 v[134:137], v0 offset:1024
	ds_read_b128 v[138:141], v0 offset:2048
	ds_read_b128 v[142:145], v0 offset:3072
.LBB0_1209:
	s_add_u32 s87, s88, 0xfffc0080
	s_addc_u32 s90, s89, -1
	s_waitcnt lgkmcnt(0)
	s_cmp_eq_u32 s85, 12
	s_cselect_b32 s93, s13, s90
	s_cselect_b32 s92, s22, s87
	s_cselect_b32 s91, s7, s79
	s_cselect_b32 s90, s23, s34
	v_lshl_add_u64 v[194:195], s[88:89], 0, v[154:155]
	s_add_i32 m0, s39, 0xc000
	ds_read_b128 v[158:161], v171
	ds_read_b128 v[162:165], v171 offset:1024
	ds_read_b128 v[166:169], v171 offset:2048
	ds_read_b128 v[172:175], v171 offset:3072
	ds_read_b128 v[176:179], v171 offset:4096
	ds_read_b128 v[180:183], v171 offset:5120
	ds_read_b128 v[184:187], v171 offset:6144
	ds_read_b128 v[190:193], v171 offset:7168
	global_load_lds_dwordx4 v[194:195], off
	s_add_i32 m0, s39, 0xe000
	v_lshl_add_u64 v[194:195], s[88:89], 0, v[156:157]
	global_load_lds_dwordx4 v[194:195], off
	s_waitcnt lgkmcnt(8)
	s_barrier
	s_waitcnt lgkmcnt(0)
	v_mfma_f32_16x16x32_bf16 v[126:129], v[130:133], v[158:161], v[126:129]
	v_mfma_f32_16x16x32_bf16 v[122:125], v[138:141], v[158:161], v[122:125]
	v_mfma_f32_16x16x32_bf16 v[110:113], v[130:133], v[166:169], v[110:113]
	v_mfma_f32_16x16x32_bf16 v[106:109], v[138:141], v[166:169], v[106:109]
	v_mfma_f32_16x16x32_bf16 v[94:97], v[130:133], v[176:179], v[94:97]
	v_mfma_f32_16x16x32_bf16 v[90:93], v[138:141], v[176:179], v[90:93]
	v_mfma_f32_16x16x32_bf16 v[78:81], v[130:133], v[184:187], v[78:81]
	v_mfma_f32_16x16x32_bf16 v[74:77], v[138:141], v[184:187], v[74:77]
	v_mfma_f32_16x16x32_bf16 v[126:129], v[134:137], v[162:165], v[126:129]
	v_mfma_f32_16x16x32_bf16 v[122:125], v[142:145], v[162:165], v[122:125]
	v_mfma_f32_16x16x32_bf16 v[110:113], v[134:137], v[172:175], v[110:113]
	v_mfma_f32_16x16x32_bf16 v[106:109], v[142:145], v[172:175], v[106:109]
	v_mfma_f32_16x16x32_bf16 v[94:97], v[134:137], v[180:183], v[94:97]
	v_mfma_f32_16x16x32_bf16 v[90:93], v[142:145], v[180:183], v[90:93]
	v_mfma_f32_16x16x32_bf16 v[78:81], v[134:137], v[190:193], v[78:81]
	v_mfma_f32_16x16x32_bf16 v[74:77], v[142:145], v[190:193], v[74:77]
	s_barrier
	s_add_i32 s87, 0, 0x14000
	s_add_i32 s94, s94, s38
	v_add_u32_e32 v0, s87, v170
	v_lshl_add_u64 v[210:211], s[90:91], 0, v[148:149]
	s_mov_b32 m0, s94
	ds_read_b128 v[194:197], v0
	ds_read_b128 v[198:201], v0 offset:1024
	ds_read_b128 v[202:205], v0 offset:2048
	ds_read_b128 v[206:209], v0 offset:3072
	global_load_lds_dwordx4 v[210:211], off
	s_add_i32 m0, s94, 0x2000
	v_lshl_add_u64 v[212:213], s[90:91], 0, v[152:153]
	global_load_lds_dwordx4 v[212:213], off
	s_barrier
	s_waitcnt lgkmcnt(0)
	v_mfma_f32_16x16x32_bf16 v[118:121], v[194:197], v[158:161], v[118:121]
	v_mfma_f32_16x16x32_bf16 v[114:117], v[202:205], v[158:161], v[114:117]
	v_mfma_f32_16x16x32_bf16 v[102:105], v[194:197], v[166:169], v[102:105]
	v_mfma_f32_16x16x32_bf16 v[98:101], v[202:205], v[166:169], v[98:101]
	v_mfma_f32_16x16x32_bf16 v[86:89], v[194:197], v[176:179], v[86:89]
	v_mfma_f32_16x16x32_bf16 v[82:85], v[202:205], v[176:179], v[82:85]
	v_mfma_f32_16x16x32_bf16 v[70:73], v[194:197], v[184:187], v[70:73]
	v_mfma_f32_16x16x32_bf16 v[66:69], v[202:205], v[184:187], v[66:69]
	v_mfma_f32_16x16x32_bf16 v[118:121], v[198:201], v[162:165], v[118:121]
	v_mfma_f32_16x16x32_bf16 v[114:117], v[206:209], v[162:165], v[114:117]
	v_mfma_f32_16x16x32_bf16 v[102:105], v[198:201], v[172:175], v[102:105]
	v_mfma_f32_16x16x32_bf16 v[98:101], v[206:209], v[172:175], v[98:101]
	v_mfma_f32_16x16x32_bf16 v[86:89], v[198:201], v[180:183], v[86:89]
	v_mfma_f32_16x16x32_bf16 v[82:85], v[206:209], v[180:183], v[82:85]
	v_mfma_f32_16x16x32_bf16 v[70:73], v[198:201], v[190:193], v[70:73]
	v_mfma_f32_16x16x32_bf16 v[66:69], v[206:209], v[190:193], v[66:69]
	s_mov_b32 m0, s39
	v_lshl_add_u64 v[214:215], s[92:93], 0, v[146:147]
	s_barrier
	ds_read_b128 v[158:161], v171 offset:16384
	ds_read_b128 v[162:165], v171 offset:17408
	ds_read_b128 v[166:169], v171 offset:18432
	ds_read_b128 v[172:175], v171 offset:19456
	ds_read_b128 v[176:179], v171 offset:20480
	ds_read_b128 v[180:183], v171 offset:21504
	ds_read_b128 v[184:187], v171 offset:22528
	ds_read_b128 v[190:193], v171 offset:23552
	global_load_lds_dwordx4 v[214:215], off
	s_mov_b32 m0, s42
	v_lshl_add_u64 v[216:217], s[92:93], 0, v[150:151]
	global_load_lds_dwordx4 v[216:217], off
	s_waitcnt vmcnt(10)
	s_barrier
	s_waitcnt lgkmcnt(0)
	v_mfma_f32_16x16x32_bf16 v[62:65], v[130:133], v[158:161], v[62:65]
	v_mfma_f32_16x16x32_bf16 v[58:61], v[138:141], v[158:161], v[58:61]
	v_mfma_f32_16x16x32_bf16 v[46:49], v[130:133], v[166:169], v[46:49]
	v_mfma_f32_16x16x32_bf16 v[42:45], v[138:141], v[166:169], v[42:45]
	v_mfma_f32_16x16x32_bf16 v[30:33], v[130:133], v[176:179], v[30:33]
	v_mfma_f32_16x16x32_bf16 v[26:29], v[138:141], v[176:179], v[26:29]
	v_mfma_f32_16x16x32_bf16 v[14:17], v[130:133], v[184:187], v[14:17]
	v_mfma_f32_16x16x32_bf16 v[10:13], v[138:141], v[184:187], v[10:13]
	v_mfma_f32_16x16x32_bf16 v[62:65], v[134:137], v[162:165], v[62:65]
	v_mfma_f32_16x16x32_bf16 v[58:61], v[142:145], v[162:165], v[58:61]
	v_mfma_f32_16x16x32_bf16 v[46:49], v[134:137], v[172:175], v[46:49]
	v_mfma_f32_16x16x32_bf16 v[42:45], v[142:145], v[172:175], v[42:45]
	v_mfma_f32_16x16x32_bf16 v[30:33], v[134:137], v[180:183], v[30:33]
	v_mfma_f32_16x16x32_bf16 v[26:29], v[142:145], v[180:183], v[26:29]
	v_mfma_f32_16x16x32_bf16 v[14:17], v[134:137], v[190:193], v[14:17]
	v_mfma_f32_16x16x32_bf16 v[10:13], v[142:145], v[190:193], v[10:13]
	s_barrier
	s_add_u32 s94, s90, 0x40000
	s_addc_u32 s95, s91, 0
	s_add_i32 s87, s87, s38
	s_mov_b32 m0, s87
	v_lshl_add_u64 v[130:131], s[94:95], 0, v[148:149]
	global_load_lds_dwordx4 v[130:131], off
	s_add_i32 m0, s87, 0x2000
	v_lshl_add_u64 v[130:131], s[94:95], 0, v[152:153]
	global_load_lds_dwordx4 v[130:131], off
	s_add_i32 s87, 0, 0x18000
	v_add_u32_e32 v0, s87, v170
	ds_read_b128 v[130:133], v0
	ds_read_b128 v[134:137], v0 offset:1024
	ds_read_b128 v[138:141], v0 offset:2048
	ds_read_b128 v[142:145], v0 offset:3072
	s_waitcnt vmcnt(6)
	s_barrier
	v_mfma_f32_16x16x32_bf16 v[54:57], v[194:197], v[158:161], v[54:57]
	v_mfma_f32_16x16x32_bf16 v[50:53], v[202:205], v[158:161], v[50:53]
	v_mfma_f32_16x16x32_bf16 v[38:41], v[194:197], v[166:169], v[38:41]
	v_mfma_f32_16x16x32_bf16 v[34:37], v[202:205], v[166:169], v[34:37]
	v_mfma_f32_16x16x32_bf16 v[22:25], v[194:197], v[176:179], v[22:25]
	v_mfma_f32_16x16x32_bf16 v[18:21], v[202:205], v[176:179], v[18:21]
	v_mfma_f32_16x16x32_bf16 v[6:9], v[194:197], v[184:187], v[6:9]
	v_mfma_f32_16x16x32_bf16 v[2:5], v[202:205], v[184:187], v[2:5]
	v_mfma_f32_16x16x32_bf16 v[54:57], v[198:201], v[162:165], v[54:57]
	v_mfma_f32_16x16x32_bf16 v[50:53], v[206:209], v[162:165], v[50:53]
	v_mfma_f32_16x16x32_bf16 v[38:41], v[198:201], v[172:175], v[38:41]
	v_mfma_f32_16x16x32_bf16 v[34:37], v[206:209], v[172:175], v[34:37]
	v_mfma_f32_16x16x32_bf16 v[22:25], v[198:201], v[180:183], v[22:25]
	v_mfma_f32_16x16x32_bf16 v[18:21], v[206:209], v[180:183], v[18:21]
	v_mfma_f32_16x16x32_bf16 v[6:9], v[198:201], v[190:193], v[6:9]
	v_mfma_f32_16x16x32_bf16 v[2:5], v[206:209], v[190:193], v[2:5]
	s_barrier
	s_add_u32 s92, s92, 0x40000
	s_addc_u32 s93, s93, 0
	s_mov_b32 m0, s43
	v_lshl_add_u64 v[194:195], s[92:93], 0, v[146:147]
	ds_read_b128 v[158:161], v171 offset:32768
	ds_read_b128 v[162:165], v171 offset:33792
	ds_read_b128 v[166:169], v171 offset:34816
	ds_read_b128 v[172:175], v171 offset:35840
	ds_read_b128 v[176:179], v171 offset:36864
	ds_read_b128 v[180:183], v171 offset:37888
	ds_read_b128 v[184:187], v171 offset:38912
	ds_read_b128 v[190:193], v171 offset:39936
	global_load_lds_dwordx4 v[194:195], off
	s_mov_b32 m0, s44
	v_lshl_add_u64 v[194:195], s[92:93], 0, v[150:151]
	global_load_lds_dwordx4 v[194:195], off
	s_waitcnt lgkmcnt(8)
	s_barrier
	s_waitcnt lgkmcnt(0)
	v_mfma_f32_16x16x32_bf16 v[126:129], v[130:133], v[158:161], v[126:129]
	v_mfma_f32_16x16x32_bf16 v[122:125], v[138:141], v[158:161], v[122:125]
	v_mfma_f32_16x16x32_bf16 v[110:113], v[130:133], v[166:169], v[110:113]
	v_mfma_f32_16x16x32_bf16 v[106:109], v[138:141], v[166:169], v[106:109]
	v_mfma_f32_16x16x32_bf16 v[94:97], v[130:133], v[176:179], v[94:97]
	v_mfma_f32_16x16x32_bf16 v[90:93], v[138:141], v[176:179], v[90:93]
	v_mfma_f32_16x16x32_bf16 v[78:81], v[130:133], v[184:187], v[78:81]
	v_mfma_f32_16x16x32_bf16 v[74:77], v[138:141], v[184:187], v[74:77]
	v_mfma_f32_16x16x32_bf16 v[126:129], v[134:137], v[162:165], v[126:129]
	v_mfma_f32_16x16x32_bf16 v[122:125], v[142:145], v[162:165], v[122:125]
	v_mfma_f32_16x16x32_bf16 v[110:113], v[134:137], v[172:175], v[110:113]
	v_mfma_f32_16x16x32_bf16 v[106:109], v[142:145], v[172:175], v[106:109]
	v_mfma_f32_16x16x32_bf16 v[94:97], v[134:137], v[180:183], v[94:97]
	v_mfma_f32_16x16x32_bf16 v[90:93], v[142:145], v[180:183], v[90:93]
	v_mfma_f32_16x16x32_bf16 v[78:81], v[134:137], v[190:193], v[78:81]
	v_mfma_f32_16x16x32_bf16 v[74:77], v[142:145], v[190:193], v[74:77]
	s_barrier
	s_add_i32 s92, 0, 0x1c000
	s_add_i32 s87, s87, s38
	v_add_u32_e32 v0, s92, v170
	v_lshl_add_u64 v[210:211], v[210:211], 0, s[40:41]
	s_mov_b32 m0, s87
	ds_read_b128 v[194:197], v0
	ds_read_b128 v[198:201], v0 offset:1024
	ds_read_b128 v[202:205], v0 offset:2048
	ds_read_b128 v[206:209], v0 offset:3072
	global_load_lds_dwordx4 v[210:211], off
	s_add_i32 m0, s87, 0x2000
	v_lshl_add_u64 v[210:211], v[212:213], 0, s[40:41]
	global_load_lds_dwordx4 v[210:211], off
	s_barrier
	s_waitcnt lgkmcnt(0)
	v_mfma_f32_16x16x32_bf16 v[118:121], v[194:197], v[158:161], v[118:121]
	v_mfma_f32_16x16x32_bf16 v[114:117], v[202:205], v[158:161], v[114:117]
	v_mfma_f32_16x16x32_bf16 v[102:105], v[194:197], v[166:169], v[102:105]
	v_mfma_f32_16x16x32_bf16 v[98:101], v[202:205], v[166:169], v[98:101]
	v_mfma_f32_16x16x32_bf16 v[86:89], v[194:197], v[176:179], v[86:89]
	v_mfma_f32_16x16x32_bf16 v[82:85], v[202:205], v[176:179], v[82:85]
	v_mfma_f32_16x16x32_bf16 v[70:73], v[194:197], v[184:187], v[70:73]
	v_mfma_f32_16x16x32_bf16 v[66:69], v[202:205], v[184:187], v[66:69]
	v_mfma_f32_16x16x32_bf16 v[118:121], v[198:201], v[162:165], v[118:121]
	v_mfma_f32_16x16x32_bf16 v[114:117], v[206:209], v[162:165], v[114:117]
	v_mfma_f32_16x16x32_bf16 v[102:105], v[198:201], v[172:175], v[102:105]
	v_mfma_f32_16x16x32_bf16 v[98:101], v[206:209], v[172:175], v[98:101]
	v_mfma_f32_16x16x32_bf16 v[86:89], v[198:201], v[180:183], v[86:89]
	v_mfma_f32_16x16x32_bf16 v[82:85], v[206:209], v[180:183], v[82:85]
	v_mfma_f32_16x16x32_bf16 v[70:73], v[198:201], v[190:193], v[70:73]
	v_mfma_f32_16x16x32_bf16 v[66:69], v[206:209], v[190:193], v[66:69]
	s_mov_b32 m0, s60
	v_lshl_add_u64 v[210:211], v[214:215], 0, s[40:41]
	s_barrier
	ds_read_b128 v[158:161], v171 offset:49152
	ds_read_b128 v[162:165], v171 offset:50176
	ds_read_b128 v[166:169], v171 offset:51200
	ds_read_b128 v[172:175], v171 offset:52224
	ds_read_b128 v[176:179], v171 offset:53248
	ds_read_b128 v[180:183], v171 offset:54272
	ds_read_b128 v[184:187], v171 offset:55296
	ds_read_b128 v[190:193], v171 offset:56320
	global_load_lds_dwordx4 v[210:211], off
	s_mov_b32 m0, s61
	v_lshl_add_u64 v[210:211], v[216:217], 0, s[40:41]
	global_load_lds_dwordx4 v[210:211], off
	s_waitcnt vmcnt(10)
	s_barrier
	s_waitcnt lgkmcnt(0)
	v_mfma_f32_16x16x32_bf16 v[62:65], v[130:133], v[158:161], v[62:65]
	v_mfma_f32_16x16x32_bf16 v[58:61], v[138:141], v[158:161], v[58:61]
	v_mfma_f32_16x16x32_bf16 v[46:49], v[130:133], v[166:169], v[46:49]
	v_mfma_f32_16x16x32_bf16 v[42:45], v[138:141], v[166:169], v[42:45]
	v_mfma_f32_16x16x32_bf16 v[30:33], v[130:133], v[176:179], v[30:33]
	v_mfma_f32_16x16x32_bf16 v[26:29], v[138:141], v[176:179], v[26:29]
	v_mfma_f32_16x16x32_bf16 v[14:17], v[130:133], v[184:187], v[14:17]
	v_mfma_f32_16x16x32_bf16 v[10:13], v[138:141], v[184:187], v[10:13]
	v_mfma_f32_16x16x32_bf16 v[62:65], v[134:137], v[162:165], v[62:65]
	v_mfma_f32_16x16x32_bf16 v[58:61], v[142:145], v[162:165], v[58:61]
	v_mfma_f32_16x16x32_bf16 v[46:49], v[134:137], v[172:175], v[46:49]
	v_mfma_f32_16x16x32_bf16 v[42:45], v[142:145], v[172:175], v[42:45]
	v_mfma_f32_16x16x32_bf16 v[30:33], v[134:137], v[180:183], v[30:33]
	v_mfma_f32_16x16x32_bf16 v[26:29], v[142:145], v[180:183], v[26:29]
	v_mfma_f32_16x16x32_bf16 v[14:17], v[134:137], v[190:193], v[14:17]
	v_mfma_f32_16x16x32_bf16 v[10:13], v[142:145], v[190:193], v[10:13]
	s_barrier
	s_add_u32 s90, s90, 0x40080
	s_addc_u32 s91, s91, 0
	s_add_i32 s87, s92, s38
	s_mov_b32 m0, s87
	v_lshl_add_u64 v[130:131], s[90:91], 0, v[148:149]
	global_load_lds_dwordx4 v[130:131], off
	s_add_i32 m0, s87, 0x2000
	v_lshl_add_u64 v[130:131], s[90:91], 0, v[152:153]
	global_load_lds_dwordx4 v[130:131], off
	s_add_i32 s94, 0, 0x10000
	v_add_u32_e32 v0, s94, v170
	ds_read_b128 v[130:133], v0
	ds_read_b128 v[134:137], v0 offset:1024
	ds_read_b128 v[138:141], v0 offset:2048
	ds_read_b128 v[142:145], v0 offset:3072
	s_waitcnt vmcnt(6)
	s_barrier
	v_mfma_f32_16x16x32_bf16 v[54:57], v[194:197], v[158:161], v[54:57]
	v_mfma_f32_16x16x32_bf16 v[50:53], v[202:205], v[158:161], v[50:53]
	v_mfma_f32_16x16x32_bf16 v[38:41], v[194:197], v[166:169], v[38:41]
	v_mfma_f32_16x16x32_bf16 v[34:37], v[202:205], v[166:169], v[34:37]
	v_mfma_f32_16x16x32_bf16 v[22:25], v[194:197], v[176:179], v[22:25]
	v_mfma_f32_16x16x32_bf16 v[18:21], v[202:205], v[176:179], v[18:21]
	v_mfma_f32_16x16x32_bf16 v[6:9], v[194:197], v[184:187], v[6:9]
	v_mfma_f32_16x16x32_bf16 v[2:5], v[202:205], v[184:187], v[2:5]
	v_mfma_f32_16x16x32_bf16 v[54:57], v[198:201], v[162:165], v[54:57]
	v_mfma_f32_16x16x32_bf16 v[50:53], v[206:209], v[162:165], v[50:53]
	v_mfma_f32_16x16x32_bf16 v[38:41], v[198:201], v[172:175], v[38:41]
	v_mfma_f32_16x16x32_bf16 v[34:37], v[206:209], v[172:175], v[34:37]
	v_mfma_f32_16x16x32_bf16 v[22:25], v[198:201], v[180:183], v[22:25]
	v_mfma_f32_16x16x32_bf16 v[18:21], v[206:209], v[180:183], v[18:21]
	v_mfma_f32_16x16x32_bf16 v[6:9], v[198:201], v[190:193], v[6:9]
	v_mfma_f32_16x16x32_bf16 v[2:5], v[206:209], v[190:193], v[2:5]
	s_add_i32 s85, s85, 2
	s_add_u32 s88, s88, 0x100
	s_addc_u32 s89, s89, 0
	s_add_u32 s34, s34, 0x100
	s_addc_u32 s79, s79, 0
	s_cmp_gt_u32 s85, 13
	s_barrier
	s_cbranch_scc0 .LBB0_1209
	s_waitcnt lgkmcnt(0)
	v_mov_b32_e32 v131, v252
	s_lshl_b32 s7, s86, 8
	v_and_b32_e32 v130, 63, v131
	v_or_b32_e32 v0, s72, v130
	v_lshrrev_b32_e32 v0, 1, v0
	v_and_or_b32 v132, v0, 63, s73
	v_add_u32_e32 v134, s7, v132
	v_ashrrev_i32_e32 v135, 31, v134
	v_and_b32_e32 v142, 1, v131
	v_lshlrev_b64 v[134:135], 6, v[134:135]
	v_lshl_add_u64 v[134:135], s[82:83], 0, v[134:135]
	v_lshlrev_b32_e32 v0, 5, v142
	v_lshl_add_u64 v[138:139], v[134:135], 0, v[0:1]
	global_load_dwordx4 v[134:137], v[138:139], off
	s_nop 0
	global_load_dwordx4 v[138:141], v[138:139], off offset:16
	v_lshlrev_b32_e32 v0, 2, v130
	v_cmp_eq_u32_e32 vcc, 0, v142
	s_waitcnt vmcnt(0)
	v_add_f32_e32 v133, v134, v135
	v_add_f32_e32 v134, v136, v137
	v_add_f32_e32 v135, v138, v139
	v_add_f32_e32 v136, v140, v141
	v_add_f32_e32 v133, v133, v134
	v_add_f32_e32 v134, v135, v136
	v_add_f32_e32 v133, v133, v134
	v_xor_b32_e32 v134, 4, v0
	ds_bpermute_b32 v134, v134, v133
	s_and_saveexec_b64 s[22:23], vcc
	s_cbranch_execz .LBB0_1212
	s_waitcnt lgkmcnt(0)
	v_add_f32_e32 v133, v133, v134
	v_fmamk_f32 v133, v133, 0x3a800000, v224
	s_mov_b32 s13, 0x800000
	v_mul_f32_e32 v134, 0x4b800000, v133
	v_cmp_gt_f32_e32 vcc, s13, v133
	v_lshl_add_u32 v132, v132, 2, 0
	v_add_u32_e32 v132, 0x20000, v132
	v_cndmask_b32_e32 v133, v133, v134, vcc
	v_rsq_f32_e32 v133, v133
	s_nop 0
	v_mul_f32_e32 v134, 0x45800000, v133
	v_cndmask_b32_e32 v133, v133, v134, vcc
	ds_write_b32 v132, v133
